# combo2 + GEMM K-loops: per-block s_setprio flips deleted, one static s_setprio 1 for waves 4-7 before each K-loop (reset after)
# speedup vs baseline: 1.0022x; 1.0022x over previous
.LBB0_218:
	s_ashr_i32 s27, s26, 31
	s_lshl_b64 s[4:5], s[26:27], 20
	s_add_u32 s30, s48, s4
	s_addc_u32 s31, s49, s5
	s_and_b64 s[4:5], s[36:37], exec
	s_cselect_b32 s4, s31, s43
	s_cselect_b32 s5, s30, s42
	s_ashr_i32 s23, s22, 31
	s_lshl_b64 s[38:39], s[22:23], 20
	s_add_u32 s38, s24, s38
	s_addc_u32 s39, s50, s39
	s_and_b64 s[46:47], s[36:37], exec
	s_cselect_b32 s23, s39, s35
	s_cselect_b32 s27, s38, s34
	s_add_u32 s61, s34, 0x100
	s_addc_u32 s62, s35, 0
	s_add_u32 s42, s42, 0x80080
	v_mov_b32_e32 v0, 0
	s_addc_u32 s43, s43, 0
	s_mov_b32 s63, -2
	v_mov_b32_e32 v1, v0
	v_mov_b32_e32 v2, v0
	v_mov_b32_e32 v3, v0
	v_mov_b32_e32 v8, v0
	v_mov_b32_e32 v9, v0
	v_mov_b32_e32 v10, v0
	v_mov_b32_e32 v11, v0
	v_mov_b32_e32 v18, v0
	v_mov_b32_e32 v19, v0
	v_mov_b32_e32 v20, v0
	v_mov_b32_e32 v21, v0
	v_mov_b32_e32 v26, v0
	v_mov_b32_e32 v27, v0
	v_mov_b32_e32 v28, v0
	v_mov_b32_e32 v29, v0
	v_mov_b32_e32 v34, v0
	v_mov_b32_e32 v35, v0
	v_mov_b32_e32 v36, v0
	v_mov_b32_e32 v37, v0
	v_mov_b32_e32 v42, v0
	v_mov_b32_e32 v43, v0
	v_mov_b32_e32 v44, v0
	v_mov_b32_e32 v45, v0
	v_mov_b32_e32 v50, v0
	v_mov_b32_e32 v51, v0
	v_mov_b32_e32 v52, v0
	v_mov_b32_e32 v53, v0
	v_mov_b32_e32 v58, v0
	v_mov_b32_e32 v59, v0
	v_mov_b32_e32 v60, v0
	v_mov_b32_e32 v61, v0
	v_mov_b32_e32 v4, v0
	v_mov_b32_e32 v5, v0
	v_mov_b32_e32 v6, v0
	v_mov_b32_e32 v7, v0
	v_mov_b32_e32 v12, v0
	v_mov_b32_e32 v13, v0
	v_mov_b32_e32 v14, v0
	v_mov_b32_e32 v15, v0
	v_mov_b32_e32 v22, v0
	v_mov_b32_e32 v23, v0
	v_mov_b32_e32 v24, v0
	v_mov_b32_e32 v25, v0
	v_mov_b32_e32 v30, v0
	v_mov_b32_e32 v31, v0
	v_mov_b32_e32 v32, v0
	v_mov_b32_e32 v33, v0
	v_mov_b32_e32 v38, v0
	v_mov_b32_e32 v39, v0
	v_mov_b32_e32 v40, v0
	v_mov_b32_e32 v41, v0
	v_mov_b32_e32 v46, v0
	v_mov_b32_e32 v47, v0
	v_mov_b32_e32 v48, v0
	v_mov_b32_e32 v49, v0
	v_mov_b32_e32 v54, v0
	v_mov_b32_e32 v55, v0
	v_mov_b32_e32 v56, v0
	v_mov_b32_e32 v57, v0
	v_mov_b32_e32 v62, v0
	v_mov_b32_e32 v63, v0
	v_mov_b32_e32 v64, v0
	v_mov_b32_e32 v65, v0
	v_mov_b32_e32 v66, v0
	v_mov_b32_e32 v67, v0
	v_mov_b32_e32 v68, v0
	v_mov_b32_e32 v69, v0
	v_mov_b32_e32 v74, v0
	v_mov_b32_e32 v75, v0
	v_mov_b32_e32 v76, v0
	v_mov_b32_e32 v77, v0
	v_mov_b32_e32 v82, v0
	v_mov_b32_e32 v83, v0
	v_mov_b32_e32 v84, v0
	v_mov_b32_e32 v85, v0
	v_mov_b32_e32 v90, v0
	v_mov_b32_e32 v91, v0
	v_mov_b32_e32 v92, v0
	v_mov_b32_e32 v93, v0
	v_mov_b32_e32 v98, v0
	v_mov_b32_e32 v99, v0
	v_mov_b32_e32 v100, v0
	v_mov_b32_e32 v101, v0
	v_mov_b32_e32 v106, v0
	v_mov_b32_e32 v107, v0
	v_mov_b32_e32 v108, v0
	v_mov_b32_e32 v109, v0
	v_mov_b32_e32 v114, v0
	v_mov_b32_e32 v115, v0
	v_mov_b32_e32 v116, v0
	v_mov_b32_e32 v117, v0
	v_mov_b32_e32 v122, v0
	v_mov_b32_e32 v123, v0
	v_mov_b32_e32 v124, v0
	v_mov_b32_e32 v125, v0
	v_mov_b32_e32 v70, v0
	v_mov_b32_e32 v71, v0
	v_mov_b32_e32 v72, v0
	v_mov_b32_e32 v73, v0
	v_mov_b32_e32 v78, v0
	v_mov_b32_e32 v79, v0
	v_mov_b32_e32 v80, v0
	v_mov_b32_e32 v81, v0
	v_mov_b32_e32 v86, v0
	v_mov_b32_e32 v87, v0
	v_mov_b32_e32 v88, v0
	v_mov_b32_e32 v89, v0
	v_mov_b32_e32 v94, v0
	v_mov_b32_e32 v95, v0
	v_mov_b32_e32 v96, v0
	v_mov_b32_e32 v97, v0
	v_mov_b32_e32 v102, v0
	v_mov_b32_e32 v103, v0
	v_mov_b32_e32 v104, v0
	v_mov_b32_e32 v105, v0
	v_mov_b32_e32 v110, v0
	v_mov_b32_e32 v111, v0
	v_mov_b32_e32 v112, v0
	v_mov_b32_e32 v113, v0
	v_mov_b32_e32 v118, v0
	v_mov_b32_e32 v119, v0
	v_mov_b32_e32 v120, v0
	v_mov_b32_e32 v121, v0
	v_mov_b32_e32 v126, v0
	v_mov_b32_e32 v127, v0
	v_mov_b32_e32 v128, v0
	v_mov_b32_e32 v129, v0
	s_and_b64 vcc, exec, s[20:21]
	s_cbranch_vccnz .Lprio_skip_0
	s_setprio 1
.Lprio_skip_0:
.LBB0_219:
	s_add_u32 s34, s42, 0xfff80080
	s_addc_u32 s35, s43, -1
	s_add_i32 s64, 0, 0x10000
	s_cmp_eq_u32 s63, 28
	s_cselect_b32 s47, s4, s35
	s_cselect_b32 s46, s5, s34
	v_add_u32_e32 v149, s64, v146
	s_cselect_b32 s35, s23, s62
	s_cselect_b32 s34, s27, s61
	s_add_i32 s66, 0, 0x14000
	ds_read_b128 v[142:145], v149
	ds_read_b128 v[160:163], v149 offset:1024
	ds_read_b128 v[164:167], v149 offset:2048
	ds_read_b128 v[168:171], v149 offset:3072
	v_add_u32_e32 v149, s66, v146
	ds_read_b128 v[172:175], v149
	ds_read_b128 v[176:179], v149 offset:1024
	ds_read_b128 v[180:183], v149 offset:2048
	ds_read_b128 v[212:215], v149 offset:3072
	v_lshl_add_u64 v[150:151], s[42:43], 0, v[140:141]
	s_add_i32 m0, s41, 0xc000
	ds_read_b128 v[216:219], v148
	ds_read_b128 v[220:223], v148 offset:1024
	ds_read_b128 v[224:227], v148 offset:2048
	ds_read_b128 v[228:231], v148 offset:3072
	ds_read_b128 v[232:235], v148 offset:4096
	ds_read_b128 v[236:239], v148 offset:5120
	ds_read_b128 v[240:243], v148 offset:6144
	ds_read_b128 v[244:247], v148 offset:7168
	global_load_lds_dwordx4 v[150:151], off
	v_lshl_add_u64 v[150:151], s[42:43], 0, v[138:139]
	s_add_i32 m0, s41, 0xe000
	s_nop 0
	global_load_lds_dwordx4 v[150:151], off
	s_waitcnt vmcnt(8)
	s_waitcnt lgkmcnt(0)
	s_barrier
	s_waitcnt lgkmcnt(0)
	v_mfma_f32_16x16x32_bf16 v[126:129], v[142:145], v[216:219], v[126:129]
	v_mfma_f32_16x16x32_bf16 v[118:121], v[164:167], v[216:219], v[118:121]
	v_mfma_f32_16x16x32_bf16 v[110:113], v[142:145], v[224:227], v[110:113]
	v_mfma_f32_16x16x32_bf16 v[102:105], v[164:167], v[224:227], v[102:105]
	v_mfma_f32_16x16x32_bf16 v[94:97], v[142:145], v[232:235], v[94:97]
	v_mfma_f32_16x16x32_bf16 v[86:89], v[164:167], v[232:235], v[86:89]
	v_mfma_f32_16x16x32_bf16 v[78:81], v[142:145], v[240:243], v[78:81]
	v_mfma_f32_16x16x32_bf16 v[70:73], v[164:167], v[240:243], v[70:73]
	v_mfma_f32_16x16x32_bf16 v[126:129], v[160:163], v[220:223], v[126:129]
	v_mfma_f32_16x16x32_bf16 v[118:121], v[168:171], v[220:223], v[118:121]
	v_mfma_f32_16x16x32_bf16 v[110:113], v[160:163], v[228:231], v[110:113]
	v_mfma_f32_16x16x32_bf16 v[102:105], v[168:171], v[228:231], v[102:105]
	v_mfma_f32_16x16x32_bf16 v[94:97], v[160:163], v[236:239], v[94:97]
	v_mfma_f32_16x16x32_bf16 v[86:89], v[168:171], v[236:239], v[86:89]
	v_mfma_f32_16x16x32_bf16 v[78:81], v[160:163], v[244:247], v[78:81]
	v_mfma_f32_16x16x32_bf16 v[70:73], v[168:171], v[244:247], v[70:73]
	v_mfma_f32_16x16x32_bf16 v[122:125], v[172:175], v[216:219], v[122:125]
	v_mfma_f32_16x16x32_bf16 v[114:117], v[180:183], v[216:219], v[114:117]
	v_mfma_f32_16x16x32_bf16 v[106:109], v[172:175], v[224:227], v[106:109]
	v_mfma_f32_16x16x32_bf16 v[98:101], v[180:183], v[224:227], v[98:101]
	v_mfma_f32_16x16x32_bf16 v[90:93], v[172:175], v[232:235], v[90:93]
	v_mfma_f32_16x16x32_bf16 v[82:85], v[180:183], v[232:235], v[82:85]
	v_mfma_f32_16x16x32_bf16 v[74:77], v[172:175], v[240:243], v[74:77]
	v_mfma_f32_16x16x32_bf16 v[66:69], v[180:183], v[240:243], v[66:69]
	v_mfma_f32_16x16x32_bf16 v[122:125], v[176:179], v[220:223], v[122:125]
	v_mfma_f32_16x16x32_bf16 v[114:117], v[212:215], v[220:223], v[114:117]
	v_mfma_f32_16x16x32_bf16 v[106:109], v[176:179], v[228:231], v[106:109]
	v_mfma_f32_16x16x32_bf16 v[98:101], v[212:215], v[228:231], v[98:101]
	v_mfma_f32_16x16x32_bf16 v[90:93], v[176:179], v[236:239], v[90:93]
	v_mfma_f32_16x16x32_bf16 v[82:85], v[212:215], v[236:239], v[82:85]
	v_mfma_f32_16x16x32_bf16 v[74:77], v[176:179], v[244:247], v[74:77]
	v_mfma_f32_16x16x32_bf16 v[66:69], v[212:215], v[244:247], v[66:69]
	s_barrier
	s_add_i32 s64, s64, s51
	v_lshl_add_u64 v[150:151], s[34:35], 0, v[134:135]
	s_mov_b32 m0, s64
	ds_read_b128 v[216:219], v148 offset:16384
	ds_read_b128 v[220:223], v148 offset:17408
	ds_read_b128 v[224:227], v148 offset:18432
	ds_read_b128 v[228:231], v148 offset:19456
	ds_read_b128 v[232:235], v148 offset:20480
	ds_read_b128 v[236:239], v148 offset:21504
	ds_read_b128 v[240:243], v148 offset:22528
	ds_read_b128 v[244:247], v148 offset:23552
	global_load_lds_dwordx4 v[150:151], off
	s_add_i32 m0, s64, 0x2000
	s_add_u32 s64, s34, 0x80000
	v_lshl_add_u64 v[248:249], s[34:35], 0, v[130:131]
	s_addc_u32 s65, s35, 0
	s_add_i32 s66, s66, s51
	global_load_lds_dwordx4 v[248:249], off
	v_lshl_add_u64 v[250:251], s[64:65], 0, v[134:135]
	s_mov_b32 m0, s66
	v_lshl_add_u64 v[210:211], s[46:47], 0, v[132:133]
	global_load_lds_dwordx4 v[250:251], off
	v_lshl_add_u64 v[250:251], s[64:65], 0, v[130:131]
	s_add_i32 m0, s66, 0x2000
	s_nop 0
	global_load_lds_dwordx4 v[250:251], off
	v_lshl_add_u64 v[250:251], s[46:47], 0, v[136:137]
	s_mov_b32 m0, s41
	s_nop 0
	global_load_lds_dwordx4 v[250:251], off
	s_mov_b32 m0, s53
	s_nop 0
	global_load_lds_dwordx4 v[210:211], off
	s_waitcnt vmcnt(8)
	s_waitcnt lgkmcnt(0)
	s_barrier
	s_waitcnt lgkmcnt(0)
	v_mfma_f32_16x16x32_bf16 v[62:65], v[142:145], v[216:219], v[62:65]
	v_mfma_f32_16x16x32_bf16 v[54:57], v[164:167], v[216:219], v[54:57]
	v_mfma_f32_16x16x32_bf16 v[46:49], v[142:145], v[224:227], v[46:49]
	v_mfma_f32_16x16x32_bf16 v[38:41], v[164:167], v[224:227], v[38:41]
	v_mfma_f32_16x16x32_bf16 v[30:33], v[142:145], v[232:235], v[30:33]
	v_mfma_f32_16x16x32_bf16 v[22:25], v[164:167], v[232:235], v[22:25]
	v_mfma_f32_16x16x32_bf16 v[12:15], v[142:145], v[240:243], v[12:15]
	v_mfma_f32_16x16x32_bf16 v[4:7], v[164:167], v[240:243], v[4:7]
	v_mfma_f32_16x16x32_bf16 v[62:65], v[160:163], v[220:223], v[62:65]
	v_mfma_f32_16x16x32_bf16 v[54:57], v[168:171], v[220:223], v[54:57]
	v_mfma_f32_16x16x32_bf16 v[46:49], v[160:163], v[228:231], v[46:49]
	v_mfma_f32_16x16x32_bf16 v[38:41], v[168:171], v[228:231], v[38:41]
	v_mfma_f32_16x16x32_bf16 v[30:33], v[160:163], v[236:239], v[30:33]
	v_mfma_f32_16x16x32_bf16 v[22:25], v[168:171], v[236:239], v[22:25]
	v_mfma_f32_16x16x32_bf16 v[12:15], v[160:163], v[244:247], v[12:15]
	v_mfma_f32_16x16x32_bf16 v[4:7], v[168:171], v[244:247], v[4:7]
	v_mfma_f32_16x16x32_bf16 v[58:61], v[172:175], v[216:219], v[58:61]
	v_mfma_f32_16x16x32_bf16 v[50:53], v[180:183], v[216:219], v[50:53]
	v_mfma_f32_16x16x32_bf16 v[42:45], v[172:175], v[224:227], v[42:45]
	v_mfma_f32_16x16x32_bf16 v[34:37], v[180:183], v[224:227], v[34:37]
	v_mfma_f32_16x16x32_bf16 v[26:29], v[172:175], v[232:235], v[26:29]
	v_mfma_f32_16x16x32_bf16 v[18:21], v[180:183], v[232:235], v[18:21]
	v_mfma_f32_16x16x32_bf16 v[8:11], v[172:175], v[240:243], v[8:11]
	v_mfma_f32_16x16x32_bf16 v[0:3], v[180:183], v[240:243], v[0:3]
	v_mfma_f32_16x16x32_bf16 v[58:61], v[176:179], v[220:223], v[58:61]
	v_mfma_f32_16x16x32_bf16 v[50:53], v[212:215], v[220:223], v[50:53]
	v_mfma_f32_16x16x32_bf16 v[42:45], v[176:179], v[228:231], v[42:45]
	v_mfma_f32_16x16x32_bf16 v[34:37], v[212:215], v[228:231], v[34:37]
	v_mfma_f32_16x16x32_bf16 v[26:29], v[176:179], v[236:239], v[26:29]
	v_mfma_f32_16x16x32_bf16 v[18:21], v[212:215], v[236:239], v[18:21]
	v_mfma_f32_16x16x32_bf16 v[8:11], v[176:179], v[244:247], v[8:11]
	v_mfma_f32_16x16x32_bf16 v[0:3], v[212:215], v[244:247], v[0:3]
	s_barrier
	s_add_i32 s64, 0, 0x18000
	v_add_u32_e32 v149, s64, v146
	s_add_i32 s65, 0, 0x1c000
	ds_read_b128 v[142:145], v149
	ds_read_b128 v[160:163], v149 offset:1024
	ds_read_b128 v[164:167], v149 offset:2048
	ds_read_b128 v[168:171], v149 offset:3072
	v_add_u32_e32 v149, s65, v146
	ds_read_b128 v[172:175], v149
	ds_read_b128 v[176:179], v149 offset:1024
	ds_read_b128 v[180:183], v149 offset:2048
	ds_read_b128 v[212:215], v149 offset:3072
	s_add_u32 s46, s46, 0x80000
	s_addc_u32 s47, s47, 0
	s_mov_b32 m0, s54
	v_lshl_add_u64 v[152:153], s[46:47], 0, v[136:137]
	ds_read_b128 v[216:219], v148 offset:32768
	ds_read_b128 v[220:223], v148 offset:33792
	ds_read_b128 v[224:227], v148 offset:34816
	ds_read_b128 v[228:231], v148 offset:35840
	ds_read_b128 v[232:235], v148 offset:36864
	ds_read_b128 v[236:239], v148 offset:37888
	ds_read_b128 v[240:243], v148 offset:38912
	ds_read_b128 v[244:247], v148 offset:39936
	global_load_lds_dwordx4 v[152:153], off
	v_lshl_add_u64 v[152:153], s[46:47], 0, v[132:133]
	s_mov_b32 m0, s55
	s_nop 0
	global_load_lds_dwordx4 v[152:153], off
	s_waitcnt vmcnt(8)
	s_waitcnt lgkmcnt(0)
	s_barrier
	s_waitcnt lgkmcnt(0)
	v_mfma_f32_16x16x32_bf16 v[126:129], v[142:145], v[216:219], v[126:129]
	v_mfma_f32_16x16x32_bf16 v[118:121], v[164:167], v[216:219], v[118:121]
	v_mfma_f32_16x16x32_bf16 v[110:113], v[142:145], v[224:227], v[110:113]
	v_mfma_f32_16x16x32_bf16 v[102:105], v[164:167], v[224:227], v[102:105]
	v_mfma_f32_16x16x32_bf16 v[94:97], v[142:145], v[232:235], v[94:97]
	v_mfma_f32_16x16x32_bf16 v[86:89], v[164:167], v[232:235], v[86:89]
	v_mfma_f32_16x16x32_bf16 v[78:81], v[142:145], v[240:243], v[78:81]
	v_mfma_f32_16x16x32_bf16 v[70:73], v[164:167], v[240:243], v[70:73]
	v_mfma_f32_16x16x32_bf16 v[126:129], v[160:163], v[220:223], v[126:129]
	v_mfma_f32_16x16x32_bf16 v[118:121], v[168:171], v[220:223], v[118:121]
	v_mfma_f32_16x16x32_bf16 v[110:113], v[160:163], v[228:231], v[110:113]
	v_mfma_f32_16x16x32_bf16 v[102:105], v[168:171], v[228:231], v[102:105]
	v_mfma_f32_16x16x32_bf16 v[94:97], v[160:163], v[236:239], v[94:97]
	v_mfma_f32_16x16x32_bf16 v[86:89], v[168:171], v[236:239], v[86:89]
	v_mfma_f32_16x16x32_bf16 v[78:81], v[160:163], v[244:247], v[78:81]
	v_mfma_f32_16x16x32_bf16 v[70:73], v[168:171], v[244:247], v[70:73]
	v_mfma_f32_16x16x32_bf16 v[122:125], v[172:175], v[216:219], v[122:125]
	v_mfma_f32_16x16x32_bf16 v[114:117], v[180:183], v[216:219], v[114:117]
	v_mfma_f32_16x16x32_bf16 v[106:109], v[172:175], v[224:227], v[106:109]
	v_mfma_f32_16x16x32_bf16 v[98:101], v[180:183], v[224:227], v[98:101]
	v_mfma_f32_16x16x32_bf16 v[90:93], v[172:175], v[232:235], v[90:93]
	v_mfma_f32_16x16x32_bf16 v[82:85], v[180:183], v[232:235], v[82:85]
	v_mfma_f32_16x16x32_bf16 v[74:77], v[172:175], v[240:243], v[74:77]
	v_mfma_f32_16x16x32_bf16 v[66:69], v[180:183], v[240:243], v[66:69]
	v_mfma_f32_16x16x32_bf16 v[122:125], v[176:179], v[220:223], v[122:125]
	v_mfma_f32_16x16x32_bf16 v[114:117], v[212:215], v[220:223], v[114:117]
	v_mfma_f32_16x16x32_bf16 v[106:109], v[176:179], v[228:231], v[106:109]
	v_mfma_f32_16x16x32_bf16 v[98:101], v[212:215], v[228:231], v[98:101]
	v_mfma_f32_16x16x32_bf16 v[90:93], v[176:179], v[236:239], v[90:93]
	v_mfma_f32_16x16x32_bf16 v[82:85], v[212:215], v[236:239], v[82:85]
	v_mfma_f32_16x16x32_bf16 v[74:77], v[176:179], v[244:247], v[74:77]
	v_mfma_f32_16x16x32_bf16 v[66:69], v[212:215], v[244:247], v[66:69]
	s_barrier
	s_add_i32 s46, s64, s51
	v_lshl_add_u64 v[150:151], v[150:151], 0, s[96:97]
	s_mov_b32 m0, s46
	ds_read_b128 v[216:219], v148 offset:49152
	ds_read_b128 v[220:223], v148 offset:50176
	ds_read_b128 v[224:227], v148 offset:51200
	ds_read_b128 v[228:231], v148 offset:52224
	ds_read_b128 v[232:235], v148 offset:53248
	ds_read_b128 v[236:239], v148 offset:54272
	ds_read_b128 v[240:243], v148 offset:55296
	ds_read_b128 v[244:247], v148 offset:56320
	global_load_lds_dwordx4 v[150:151], off
	s_add_i32 m0, s46, 0x2000
	s_add_u32 s34, s34, 0x80080
	v_lshl_add_u64 v[150:151], v[248:249], 0, s[96:97]
	s_addc_u32 s35, s35, 0
	s_add_i32 s46, s65, s51
	global_load_lds_dwordx4 v[150:151], off
	v_lshl_add_u64 v[150:151], s[34:35], 0, v[134:135]
	s_mov_b32 m0, s46
	s_nop 0
	global_load_lds_dwordx4 v[150:151], off
	v_lshl_add_u64 v[150:151], s[34:35], 0, v[130:131]
	s_add_i32 m0, s46, 0x2000
	s_nop 0
	global_load_lds_dwordx4 v[150:151], off
	v_lshl_add_u64 v[150:151], v[250:251], 0, s[96:97]
	s_mov_b32 m0, s56
	s_nop 0
	global_load_lds_dwordx4 v[150:151], off
	v_lshl_add_u64 v[150:151], v[210:211], 0, s[96:97]
	s_mov_b32 m0, s57
	s_nop 0
	global_load_lds_dwordx4 v[150:151], off
	s_waitcnt vmcnt(8)
	s_waitcnt lgkmcnt(0)
	s_barrier
	s_waitcnt lgkmcnt(0)
	v_mfma_f32_16x16x32_bf16 v[62:65], v[142:145], v[216:219], v[62:65]
	v_mfma_f32_16x16x32_bf16 v[54:57], v[164:167], v[216:219], v[54:57]
	v_mfma_f32_16x16x32_bf16 v[46:49], v[142:145], v[224:227], v[46:49]
	v_mfma_f32_16x16x32_bf16 v[38:41], v[164:167], v[224:227], v[38:41]
	v_mfma_f32_16x16x32_bf16 v[30:33], v[142:145], v[232:235], v[30:33]
	v_mfma_f32_16x16x32_bf16 v[22:25], v[164:167], v[232:235], v[22:25]
	v_mfma_f32_16x16x32_bf16 v[12:15], v[142:145], v[240:243], v[12:15]
	v_mfma_f32_16x16x32_bf16 v[4:7], v[164:167], v[240:243], v[4:7]
	v_mfma_f32_16x16x32_bf16 v[62:65], v[160:163], v[220:223], v[62:65]
	v_mfma_f32_16x16x32_bf16 v[54:57], v[168:171], v[220:223], v[54:57]
	v_mfma_f32_16x16x32_bf16 v[46:49], v[160:163], v[228:231], v[46:49]
	v_mfma_f32_16x16x32_bf16 v[38:41], v[168:171], v[228:231], v[38:41]
	v_mfma_f32_16x16x32_bf16 v[30:33], v[160:163], v[236:239], v[30:33]
	v_mfma_f32_16x16x32_bf16 v[22:25], v[168:171], v[236:239], v[22:25]
	v_mfma_f32_16x16x32_bf16 v[12:15], v[160:163], v[244:247], v[12:15]
	v_mfma_f32_16x16x32_bf16 v[4:7], v[168:171], v[244:247], v[4:7]
	v_mfma_f32_16x16x32_bf16 v[58:61], v[172:175], v[216:219], v[58:61]
	v_mfma_f32_16x16x32_bf16 v[50:53], v[180:183], v[216:219], v[50:53]
	v_mfma_f32_16x16x32_bf16 v[42:45], v[172:175], v[224:227], v[42:45]
	v_mfma_f32_16x16x32_bf16 v[34:37], v[180:183], v[224:227], v[34:37]
	v_mfma_f32_16x16x32_bf16 v[26:29], v[172:175], v[232:235], v[26:29]
	v_mfma_f32_16x16x32_bf16 v[18:21], v[180:183], v[232:235], v[18:21]
	v_mfma_f32_16x16x32_bf16 v[8:11], v[172:175], v[240:243], v[8:11]
	v_mfma_f32_16x16x32_bf16 v[0:3], v[180:183], v[240:243], v[0:3]
	v_mfma_f32_16x16x32_bf16 v[58:61], v[176:179], v[220:223], v[58:61]
	v_mfma_f32_16x16x32_bf16 v[50:53], v[212:215], v[220:223], v[50:53]
	v_mfma_f32_16x16x32_bf16 v[42:45], v[176:179], v[228:231], v[42:45]
	v_mfma_f32_16x16x32_bf16 v[34:37], v[212:215], v[228:231], v[34:37]
	v_mfma_f32_16x16x32_bf16 v[26:29], v[176:179], v[236:239], v[26:29]
	v_mfma_f32_16x16x32_bf16 v[18:21], v[212:215], v[236:239], v[18:21]
	v_mfma_f32_16x16x32_bf16 v[8:11], v[176:179], v[244:247], v[8:11]
	v_mfma_f32_16x16x32_bf16 v[0:3], v[212:215], v[244:247], v[0:3]
	s_barrier
	s_add_i32 s63, s63, 2
	s_add_u32 s61, s61, 0x100
	s_addc_u32 s62, s62, 0
	s_add_u32 s42, s42, 0x100
	s_addc_u32 s43, s43, 0
	s_cmp_gt_u32 s63, 29
	s_cbranch_scc0 .LBB0_219
	s_setprio 0
	s_and_b64 vcc, exec, s[20:21]
	s_cbranch_vccz .LBB0_222
	s_barrier

.LBB0_299:
	s_add_u32 s4, s34, 0x100
	v_mov_b32_e32 v0, 0
	s_addc_u32 s5, s35, 0
	s_mov_b32 s63, -2
	v_mov_b32_e32 v1, v0
	v_mov_b32_e32 v2, v0
	v_mov_b32_e32 v3, v0
	v_mov_b32_e32 v4, v0
	v_mov_b32_e32 v5, v0
	v_mov_b32_e32 v6, v0
	v_mov_b32_e32 v7, v0
	v_mov_b32_e32 v8, v0
	v_mov_b32_e32 v9, v0
	v_mov_b32_e32 v10, v0
	v_mov_b32_e32 v11, v0
	v_mov_b32_e32 v12, v0
	v_mov_b32_e32 v13, v0
	v_mov_b32_e32 v14, v0
	v_mov_b32_e32 v15, v0
	v_mov_b32_e32 v18, v0
	v_mov_b32_e32 v19, v0
	v_mov_b32_e32 v20, v0
	v_mov_b32_e32 v21, v0
	v_mov_b32_e32 v22, v0
	v_mov_b32_e32 v23, v0
	v_mov_b32_e32 v24, v0
	v_mov_b32_e32 v25, v0
	v_mov_b32_e32 v26, v0
	v_mov_b32_e32 v27, v0
	v_mov_b32_e32 v28, v0
	v_mov_b32_e32 v29, v0
	v_mov_b32_e32 v30, v0
	v_mov_b32_e32 v31, v0
	v_mov_b32_e32 v32, v0
	v_mov_b32_e32 v33, v0
	v_mov_b32_e32 v66, v0
	v_mov_b32_e32 v67, v0
	v_mov_b32_e32 v68, v0
	v_mov_b32_e32 v69, v0
	v_mov_b32_e32 v70, v0
	v_mov_b32_e32 v71, v0
	v_mov_b32_e32 v72, v0
	v_mov_b32_e32 v73, v0
	v_mov_b32_e32 v74, v0
	v_mov_b32_e32 v75, v0
	v_mov_b32_e32 v76, v0
	v_mov_b32_e32 v77, v0
	v_mov_b32_e32 v78, v0
	v_mov_b32_e32 v79, v0
	v_mov_b32_e32 v80, v0
	v_mov_b32_e32 v81, v0
	v_mov_b32_e32 v82, v0
	v_mov_b32_e32 v83, v0
	v_mov_b32_e32 v84, v0
	v_mov_b32_e32 v85, v0
	v_mov_b32_e32 v86, v0
	v_mov_b32_e32 v87, v0
	v_mov_b32_e32 v88, v0
	v_mov_b32_e32 v89, v0
	v_mov_b32_e32 v90, v0
	v_mov_b32_e32 v91, v0
	v_mov_b32_e32 v92, v0
	v_mov_b32_e32 v93, v0
	v_mov_b32_e32 v94, v0
	v_mov_b32_e32 v95, v0
	v_mov_b32_e32 v96, v0
	v_mov_b32_e32 v97, v0
	v_mov_b32_e32 v34, v0
	v_mov_b32_e32 v35, v0
	v_mov_b32_e32 v36, v0
	v_mov_b32_e32 v37, v0
	v_mov_b32_e32 v38, v0
	v_mov_b32_e32 v39, v0
	v_mov_b32_e32 v40, v0
	v_mov_b32_e32 v41, v0
	v_mov_b32_e32 v42, v0
	v_mov_b32_e32 v43, v0
	v_mov_b32_e32 v44, v0
	v_mov_b32_e32 v45, v0
	v_mov_b32_e32 v46, v0
	v_mov_b32_e32 v47, v0
	v_mov_b32_e32 v48, v0
	v_mov_b32_e32 v49, v0
	v_mov_b32_e32 v50, v0
	v_mov_b32_e32 v51, v0
	v_mov_b32_e32 v52, v0
	v_mov_b32_e32 v53, v0
	v_mov_b32_e32 v54, v0
	v_mov_b32_e32 v55, v0
	v_mov_b32_e32 v56, v0
	v_mov_b32_e32 v57, v0
	v_mov_b32_e32 v58, v0
	v_mov_b32_e32 v59, v0
	v_mov_b32_e32 v60, v0
	v_mov_b32_e32 v61, v0
	v_mov_b32_e32 v62, v0
	v_mov_b32_e32 v63, v0
	v_mov_b32_e32 v64, v0
	v_mov_b32_e32 v65, v0
	v_mov_b32_e32 v98, v0
	v_mov_b32_e32 v99, v0
	v_mov_b32_e32 v100, v0
	v_mov_b32_e32 v101, v0
	v_mov_b32_e32 v102, v0
	v_mov_b32_e32 v103, v0
	v_mov_b32_e32 v104, v0
	v_mov_b32_e32 v105, v0
	v_mov_b32_e32 v106, v0
	v_mov_b32_e32 v107, v0
	v_mov_b32_e32 v108, v0
	v_mov_b32_e32 v109, v0
	v_mov_b32_e32 v110, v0
	v_mov_b32_e32 v111, v0
	v_mov_b32_e32 v112, v0
	v_mov_b32_e32 v113, v0
	v_mov_b32_e32 v114, v0
	v_mov_b32_e32 v115, v0
	v_mov_b32_e32 v116, v0
	v_mov_b32_e32 v117, v0
	v_mov_b32_e32 v118, v0
	v_mov_b32_e32 v119, v0
	v_mov_b32_e32 v120, v0
	v_mov_b32_e32 v121, v0
	v_mov_b32_e32 v122, v0
	v_mov_b32_e32 v123, v0
	v_mov_b32_e32 v124, v0
	v_mov_b32_e32 v125, v0
	v_mov_b32_e32 v126, v0
	v_mov_b32_e32 v127, v0
	v_mov_b32_e32 v128, v0
	v_mov_b32_e32 v129, v0
	s_and_b64 vcc, exec, s[20:21]
	s_cbranch_vccnz .Lprio_skip_1
	s_setprio 1
.Lprio_skip_1:
.LBB0_300:
	s_add_u32 s34, s30, 0x100
	s_addc_u32 s35, s31, 0
	s_add_i32 s64, 0, 0x10000
	s_cmpk_eq_i32 s63, 0x54
	s_cselect_b32 s41, s23, s35
	s_cselect_b32 s40, s22, s34
	v_add_u32_e32 v150, s64, v166
	s_cselect_b32 s39, s27, s5
	s_cselect_b32 s38, s26, s4
	s_add_i32 s65, 0, 0x14000
	ds_read_b128 v[142:145], v150
	ds_read_b128 v[146:149], v150 offset:1024
	ds_read_b128 v[160:163], v150 offset:2048
	ds_read_b128 v[170:173], v150 offset:3072
	v_add_u32_e32 v150, s65, v166
	ds_read_b128 v[174:177], v150
	ds_read_b128 v[178:181], v150 offset:1024
	ds_read_b128 v[212:215], v150 offset:2048
	ds_read_b128 v[216:219], v150 offset:3072
	v_lshl_add_u64 v[150:151], s[30:31], 0, v[140:141]
	s_add_i32 m0, s50, 0xc000
	ds_read_b128 v[220:223], v168
	ds_read_b128 v[224:227], v168 offset:1024
	ds_read_b128 v[228:231], v168 offset:2048
	ds_read_b128 v[232:235], v168 offset:3072
	ds_read_b128 v[236:239], v168 offset:4096
	ds_read_b128 v[240:243], v168 offset:5120
	ds_read_b128 v[244:247], v168 offset:6144
	ds_read_b128 v[248:251], v168 offset:7168
	global_load_lds_dwordx4 v[150:151], off
	v_lshl_add_u64 v[150:151], s[30:31], 0, v[138:139]
	s_add_i32 m0, s50, 0xe000
	s_nop 0
	global_load_lds_dwordx4 v[150:151], off
	s_waitcnt vmcnt(8)
	s_waitcnt lgkmcnt(0)
	s_barrier
	s_waitcnt lgkmcnt(0)
	v_mfma_f32_16x16x32_bf16 v[126:129], v[142:145], v[220:223], v[126:129]
	v_mfma_f32_16x16x32_bf16 v[122:125], v[160:163], v[220:223], v[122:125]
	v_mfma_f32_16x16x32_bf16 v[118:121], v[142:145], v[228:231], v[118:121]
	v_mfma_f32_16x16x32_bf16 v[114:117], v[160:163], v[228:231], v[114:117]
	v_mfma_f32_16x16x32_bf16 v[110:113], v[142:145], v[236:239], v[110:113]
	v_mfma_f32_16x16x32_bf16 v[106:109], v[160:163], v[236:239], v[106:109]
	v_mfma_f32_16x16x32_bf16 v[102:105], v[142:145], v[244:247], v[102:105]
	v_mfma_f32_16x16x32_bf16 v[98:101], v[160:163], v[244:247], v[98:101]
	v_mfma_f32_16x16x32_bf16 v[126:129], v[146:149], v[224:227], v[126:129]
	v_mfma_f32_16x16x32_bf16 v[122:125], v[170:173], v[224:227], v[122:125]
	v_mfma_f32_16x16x32_bf16 v[118:121], v[146:149], v[232:235], v[118:121]
	v_mfma_f32_16x16x32_bf16 v[114:117], v[170:173], v[232:235], v[114:117]
	v_mfma_f32_16x16x32_bf16 v[110:113], v[146:149], v[240:243], v[110:113]
	v_mfma_f32_16x16x32_bf16 v[106:109], v[170:173], v[240:243], v[106:109]
	v_mfma_f32_16x16x32_bf16 v[102:105], v[146:149], v[248:251], v[102:105]
	v_mfma_f32_16x16x32_bf16 v[98:101], v[170:173], v[248:251], v[98:101]
	v_mfma_f32_16x16x32_bf16 v[62:65], v[174:177], v[220:223], v[62:65]
	v_mfma_f32_16x16x32_bf16 v[58:61], v[212:215], v[220:223], v[58:61]
	v_mfma_f32_16x16x32_bf16 v[54:57], v[174:177], v[228:231], v[54:57]
	v_mfma_f32_16x16x32_bf16 v[50:53], v[212:215], v[228:231], v[50:53]
	v_mfma_f32_16x16x32_bf16 v[46:49], v[174:177], v[236:239], v[46:49]
	v_mfma_f32_16x16x32_bf16 v[42:45], v[212:215], v[236:239], v[42:45]
	v_mfma_f32_16x16x32_bf16 v[38:41], v[174:177], v[244:247], v[38:41]
	v_mfma_f32_16x16x32_bf16 v[34:37], v[212:215], v[244:247], v[34:37]
	v_mfma_f32_16x16x32_bf16 v[62:65], v[178:181], v[224:227], v[62:65]
	v_mfma_f32_16x16x32_bf16 v[58:61], v[216:219], v[224:227], v[58:61]
	v_mfma_f32_16x16x32_bf16 v[54:57], v[178:181], v[232:235], v[54:57]
	v_mfma_f32_16x16x32_bf16 v[50:53], v[216:219], v[232:235], v[50:53]
	v_mfma_f32_16x16x32_bf16 v[46:49], v[178:181], v[240:243], v[46:49]
	v_mfma_f32_16x16x32_bf16 v[42:45], v[216:219], v[240:243], v[42:45]
	v_mfma_f32_16x16x32_bf16 v[38:41], v[178:181], v[248:251], v[38:41]
	v_mfma_f32_16x16x32_bf16 v[34:37], v[216:219], v[248:251], v[34:37]
	s_barrier
	s_add_i32 s30, s64, s49
	v_lshl_add_u64 v[150:151], s[38:39], 0, v[132:133]
	s_mov_b32 m0, s30
	ds_read_b128 v[220:223], v168 offset:16384
	ds_read_b128 v[224:227], v168 offset:17408
	ds_read_b128 v[228:231], v168 offset:18432
	ds_read_b128 v[232:235], v168 offset:19456
	ds_read_b128 v[236:239], v168 offset:20480
	ds_read_b128 v[240:243], v168 offset:21504
	ds_read_b128 v[244:247], v168 offset:22528
	ds_read_b128 v[248:251], v168 offset:23552
	global_load_lds_dwordx4 v[150:151], off
	s_add_i32 m0, s30, 0x2000
	s_add_u32 s30, s38, 0x160000
	v_lshl_add_u64 v[152:153], s[38:39], 0, v[136:137]
	s_addc_u32 s31, s39, 0
	s_add_i32 s64, s65, s49
	global_load_lds_dwordx4 v[152:153], off
	v_lshl_add_u64 v[164:165], s[30:31], 0, v[132:133]
	s_mov_b32 m0, s64
	v_lshl_add_u64 v[182:183], s[40:41], 0, v[134:135]
	global_load_lds_dwordx4 v[164:165], off
	v_lshl_add_u64 v[164:165], s[30:31], 0, v[136:137]
	s_add_i32 m0, s64, 0x2000
	s_nop 0
	global_load_lds_dwordx4 v[164:165], off
	v_lshl_add_u64 v[164:165], s[40:41], 0, v[130:131]
	s_mov_b32 m0, s50
	s_nop 0
	global_load_lds_dwordx4 v[164:165], off
	s_mov_b32 m0, s51
	s_nop 0
	global_load_lds_dwordx4 v[182:183], off
	s_waitcnt vmcnt(8)
	s_waitcnt lgkmcnt(0)
	s_barrier
	s_waitcnt lgkmcnt(0)
	v_mfma_f32_16x16x32_bf16 v[94:97], v[142:145], v[220:223], v[94:97]
	v_mfma_f32_16x16x32_bf16 v[90:93], v[160:163], v[220:223], v[90:93]
	v_mfma_f32_16x16x32_bf16 v[86:89], v[142:145], v[228:231], v[86:89]
	v_mfma_f32_16x16x32_bf16 v[82:85], v[160:163], v[228:231], v[82:85]
	v_mfma_f32_16x16x32_bf16 v[78:81], v[142:145], v[236:239], v[78:81]
	v_mfma_f32_16x16x32_bf16 v[74:77], v[160:163], v[236:239], v[74:77]
	v_mfma_f32_16x16x32_bf16 v[70:73], v[142:145], v[244:247], v[70:73]
	v_mfma_f32_16x16x32_bf16 v[66:69], v[160:163], v[244:247], v[66:69]
	v_mfma_f32_16x16x32_bf16 v[94:97], v[146:149], v[224:227], v[94:97]
	v_mfma_f32_16x16x32_bf16 v[90:93], v[170:173], v[224:227], v[90:93]
	v_mfma_f32_16x16x32_bf16 v[86:89], v[146:149], v[232:235], v[86:89]
	v_mfma_f32_16x16x32_bf16 v[82:85], v[170:173], v[232:235], v[82:85]
	v_mfma_f32_16x16x32_bf16 v[78:81], v[146:149], v[240:243], v[78:81]
	v_mfma_f32_16x16x32_bf16 v[74:77], v[170:173], v[240:243], v[74:77]
	v_mfma_f32_16x16x32_bf16 v[70:73], v[146:149], v[248:251], v[70:73]
	v_mfma_f32_16x16x32_bf16 v[66:69], v[170:173], v[248:251], v[66:69]
	v_mfma_f32_16x16x32_bf16 v[30:33], v[174:177], v[220:223], v[30:33]
	v_mfma_f32_16x16x32_bf16 v[26:29], v[212:215], v[220:223], v[26:29]
	v_mfma_f32_16x16x32_bf16 v[22:25], v[174:177], v[228:231], v[22:25]
	v_mfma_f32_16x16x32_bf16 v[18:21], v[212:215], v[228:231], v[18:21]
	v_mfma_f32_16x16x32_bf16 v[12:15], v[174:177], v[236:239], v[12:15]
	v_mfma_f32_16x16x32_bf16 v[8:11], v[212:215], v[236:239], v[8:11]
	v_mfma_f32_16x16x32_bf16 v[4:7], v[174:177], v[244:247], v[4:7]
	v_mfma_f32_16x16x32_bf16 v[0:3], v[212:215], v[244:247], v[0:3]
	v_mfma_f32_16x16x32_bf16 v[30:33], v[178:181], v[224:227], v[30:33]
	v_mfma_f32_16x16x32_bf16 v[26:29], v[216:219], v[224:227], v[26:29]
	v_mfma_f32_16x16x32_bf16 v[22:25], v[178:181], v[232:235], v[22:25]
	v_mfma_f32_16x16x32_bf16 v[18:21], v[216:219], v[232:235], v[18:21]
	v_mfma_f32_16x16x32_bf16 v[12:15], v[178:181], v[240:243], v[12:15]
	v_mfma_f32_16x16x32_bf16 v[8:11], v[216:219], v[240:243], v[8:11]
	v_mfma_f32_16x16x32_bf16 v[4:7], v[178:181], v[248:251], v[4:7]
	v_mfma_f32_16x16x32_bf16 v[0:3], v[216:219], v[248:251], v[0:3]
	s_barrier
	s_add_i32 s64, 0, 0x18000
	v_add_u32_e32 v169, s64, v166
	s_add_i32 s65, 0, 0x1c000
	ds_read_b128 v[142:145], v169
	ds_read_b128 v[146:149], v169 offset:1024
	ds_read_b128 v[160:163], v169 offset:2048
	ds_read_b128 v[170:173], v169 offset:3072
	v_add_u32_e32 v169, s65, v166
	ds_read_b128 v[174:177], v169
	ds_read_b128 v[178:181], v169 offset:1024
	ds_read_b128 v[212:215], v169 offset:2048
	ds_read_b128 v[216:219], v169 offset:3072
	s_add_u32 s30, s40, 0x160000
	s_addc_u32 s31, s41, 0
	s_mov_b32 m0, s52
	v_lshl_add_u64 v[210:211], s[30:31], 0, v[130:131]
	ds_read_b128 v[220:223], v168 offset:32768
	ds_read_b128 v[224:227], v168 offset:33792
	ds_read_b128 v[228:231], v168 offset:34816
	ds_read_b128 v[232:235], v168 offset:35840
	ds_read_b128 v[236:239], v168 offset:36864
	ds_read_b128 v[240:243], v168 offset:37888
	ds_read_b128 v[244:247], v168 offset:38912
	ds_read_b128 v[248:251], v168 offset:39936
	global_load_lds_dwordx4 v[210:211], off
	v_lshl_add_u64 v[210:211], s[30:31], 0, v[134:135]
	s_mov_b32 m0, s53
	s_nop 0
	global_load_lds_dwordx4 v[210:211], off
	s_waitcnt vmcnt(8)
	s_waitcnt lgkmcnt(0)
	s_barrier
	s_waitcnt lgkmcnt(0)
	v_mfma_f32_16x16x32_bf16 v[126:129], v[142:145], v[220:223], v[126:129]
	v_mfma_f32_16x16x32_bf16 v[122:125], v[160:163], v[220:223], v[122:125]
	v_mfma_f32_16x16x32_bf16 v[118:121], v[142:145], v[228:231], v[118:121]
	v_mfma_f32_16x16x32_bf16 v[114:117], v[160:163], v[228:231], v[114:117]
	v_mfma_f32_16x16x32_bf16 v[110:113], v[142:145], v[236:239], v[110:113]
	v_mfma_f32_16x16x32_bf16 v[106:109], v[160:163], v[236:239], v[106:109]
	v_mfma_f32_16x16x32_bf16 v[102:105], v[142:145], v[244:247], v[102:105]
	v_mfma_f32_16x16x32_bf16 v[98:101], v[160:163], v[244:247], v[98:101]
	v_mfma_f32_16x16x32_bf16 v[126:129], v[146:149], v[224:227], v[126:129]
	v_mfma_f32_16x16x32_bf16 v[122:125], v[170:173], v[224:227], v[122:125]
	v_mfma_f32_16x16x32_bf16 v[118:121], v[146:149], v[232:235], v[118:121]
	v_mfma_f32_16x16x32_bf16 v[114:117], v[170:173], v[232:235], v[114:117]
	v_mfma_f32_16x16x32_bf16 v[110:113], v[146:149], v[240:243], v[110:113]
	v_mfma_f32_16x16x32_bf16 v[106:109], v[170:173], v[240:243], v[106:109]
	v_mfma_f32_16x16x32_bf16 v[102:105], v[146:149], v[248:251], v[102:105]
	v_mfma_f32_16x16x32_bf16 v[98:101], v[170:173], v[248:251], v[98:101]
	v_mfma_f32_16x16x32_bf16 v[62:65], v[174:177], v[220:223], v[62:65]
	v_mfma_f32_16x16x32_bf16 v[58:61], v[212:215], v[220:223], v[58:61]
	v_mfma_f32_16x16x32_bf16 v[54:57], v[174:177], v[228:231], v[54:57]
	v_mfma_f32_16x16x32_bf16 v[50:53], v[212:215], v[228:231], v[50:53]
	v_mfma_f32_16x16x32_bf16 v[46:49], v[174:177], v[236:239], v[46:49]
	v_mfma_f32_16x16x32_bf16 v[42:45], v[212:215], v[236:239], v[42:45]
	v_mfma_f32_16x16x32_bf16 v[38:41], v[174:177], v[244:247], v[38:41]
	v_mfma_f32_16x16x32_bf16 v[34:37], v[212:215], v[244:247], v[34:37]
	v_mfma_f32_16x16x32_bf16 v[62:65], v[178:181], v[224:227], v[62:65]
	v_mfma_f32_16x16x32_bf16 v[58:61], v[216:219], v[224:227], v[58:61]
	v_mfma_f32_16x16x32_bf16 v[54:57], v[178:181], v[232:235], v[54:57]
	v_mfma_f32_16x16x32_bf16 v[50:53], v[216:219], v[232:235], v[50:53]
	v_mfma_f32_16x16x32_bf16 v[46:49], v[178:181], v[240:243], v[46:49]
	v_mfma_f32_16x16x32_bf16 v[42:45], v[216:219], v[240:243], v[42:45]
	v_mfma_f32_16x16x32_bf16 v[38:41], v[178:181], v[248:251], v[38:41]
	v_mfma_f32_16x16x32_bf16 v[34:37], v[216:219], v[248:251], v[34:37]
	s_barrier
	s_add_i32 s30, s64, s49
	v_lshl_add_u64 v[150:151], v[150:151], 0, s[96:97]
	s_mov_b32 m0, s30
	ds_read_b128 v[220:223], v168 offset:49152
	ds_read_b128 v[224:227], v168 offset:50176
	ds_read_b128 v[228:231], v168 offset:51200
	ds_read_b128 v[232:235], v168 offset:52224
	ds_read_b128 v[236:239], v168 offset:53248
	ds_read_b128 v[240:243], v168 offset:54272
	ds_read_b128 v[244:247], v168 offset:55296
	ds_read_b128 v[248:251], v168 offset:56320
	global_load_lds_dwordx4 v[150:151], off
	s_add_i32 m0, s30, 0x2000
	s_add_u32 s30, s38, 0x160080
	v_lshl_add_u64 v[150:151], v[152:153], 0, s[96:97]
	s_addc_u32 s31, s39, 0
	s_add_i32 s38, s65, s49
	global_load_lds_dwordx4 v[150:151], off
	v_lshl_add_u64 v[150:151], s[30:31], 0, v[132:133]
	s_mov_b32 m0, s38
	s_nop 0
	global_load_lds_dwordx4 v[150:151], off
	v_lshl_add_u64 v[150:151], s[30:31], 0, v[136:137]
	s_add_i32 m0, s38, 0x2000
	s_nop 0
	global_load_lds_dwordx4 v[150:151], off
	v_lshl_add_u64 v[150:151], v[164:165], 0, s[96:97]
	s_mov_b32 m0, s55
	s_nop 0
	global_load_lds_dwordx4 v[150:151], off
	v_lshl_add_u64 v[150:151], v[182:183], 0, s[96:97]
	s_mov_b32 m0, s56
	s_nop 0
	global_load_lds_dwordx4 v[150:151], off
	s_waitcnt vmcnt(8)
	s_waitcnt lgkmcnt(0)
	s_barrier
	s_waitcnt lgkmcnt(0)
	v_mfma_f32_16x16x32_bf16 v[94:97], v[142:145], v[220:223], v[94:97]
	v_mfma_f32_16x16x32_bf16 v[90:93], v[160:163], v[220:223], v[90:93]
	v_mfma_f32_16x16x32_bf16 v[86:89], v[142:145], v[228:231], v[86:89]
	v_mfma_f32_16x16x32_bf16 v[82:85], v[160:163], v[228:231], v[82:85]
	v_mfma_f32_16x16x32_bf16 v[78:81], v[142:145], v[236:239], v[78:81]
	v_mfma_f32_16x16x32_bf16 v[74:77], v[160:163], v[236:239], v[74:77]
	v_mfma_f32_16x16x32_bf16 v[70:73], v[142:145], v[244:247], v[70:73]
	v_mfma_f32_16x16x32_bf16 v[66:69], v[160:163], v[244:247], v[66:69]
	v_mfma_f32_16x16x32_bf16 v[94:97], v[146:149], v[224:227], v[94:97]
	v_mfma_f32_16x16x32_bf16 v[90:93], v[170:173], v[224:227], v[90:93]
	v_mfma_f32_16x16x32_bf16 v[86:89], v[146:149], v[232:235], v[86:89]
	v_mfma_f32_16x16x32_bf16 v[82:85], v[170:173], v[232:235], v[82:85]
	v_mfma_f32_16x16x32_bf16 v[78:81], v[146:149], v[240:243], v[78:81]
	v_mfma_f32_16x16x32_bf16 v[74:77], v[170:173], v[240:243], v[74:77]
	v_mfma_f32_16x16x32_bf16 v[70:73], v[146:149], v[248:251], v[70:73]
	v_mfma_f32_16x16x32_bf16 v[66:69], v[170:173], v[248:251], v[66:69]
	v_mfma_f32_16x16x32_bf16 v[30:33], v[174:177], v[220:223], v[30:33]
	v_mfma_f32_16x16x32_bf16 v[26:29], v[212:215], v[220:223], v[26:29]
	v_mfma_f32_16x16x32_bf16 v[22:25], v[174:177], v[228:231], v[22:25]
	v_mfma_f32_16x16x32_bf16 v[18:21], v[212:215], v[228:231], v[18:21]
	v_mfma_f32_16x16x32_bf16 v[12:15], v[174:177], v[236:239], v[12:15]
	v_mfma_f32_16x16x32_bf16 v[8:11], v[212:215], v[236:239], v[8:11]
	v_mfma_f32_16x16x32_bf16 v[4:7], v[174:177], v[244:247], v[4:7]
	v_mfma_f32_16x16x32_bf16 v[0:3], v[212:215], v[244:247], v[0:3]
	v_mfma_f32_16x16x32_bf16 v[30:33], v[178:181], v[224:227], v[30:33]
	v_mfma_f32_16x16x32_bf16 v[26:29], v[216:219], v[224:227], v[26:29]
	v_mfma_f32_16x16x32_bf16 v[22:25], v[178:181], v[232:235], v[22:25]
	v_mfma_f32_16x16x32_bf16 v[18:21], v[216:219], v[232:235], v[18:21]
	v_mfma_f32_16x16x32_bf16 v[12:15], v[178:181], v[240:243], v[12:15]
	v_mfma_f32_16x16x32_bf16 v[8:11], v[216:219], v[240:243], v[8:11]
	v_mfma_f32_16x16x32_bf16 v[4:7], v[178:181], v[248:251], v[4:7]
	v_mfma_f32_16x16x32_bf16 v[0:3], v[216:219], v[248:251], v[0:3]
	s_barrier
	s_add_i32 s63, s63, 2
	s_add_u32 s4, s4, 0x100
	s_addc_u32 s5, s5, 0
	s_cmpk_gt_u32 s63, 0x55
	s_mov_b64 s[30:31], s[34:35]
	s_cbranch_scc0 .LBB0_300
	s_setprio 0
	s_and_b64 vcc, exec, s[20:21]
	s_cbranch_vccz .LBB0_303
	s_barrier

.LBB0_429:
	s_ashr_i32 s27, s26, 31
	s_lshl_b64 s[4:5], s[26:27], 20
	s_add_u32 s38, s48, s4
	s_addc_u32 s39, s49, s5
	s_and_b64 s[4:5], s[36:37], exec
	s_cselect_b32 s4, s39, s43
	s_cselect_b32 s5, s38, s42
	s_ashr_i32 s23, s22, 31
	s_lshl_b64 s[40:41], s[22:23], 20
	s_add_u32 s40, s24, s40
	s_addc_u32 s41, s50, s41
	s_and_b64 s[46:47], s[36:37], exec
	s_cselect_b32 s23, s41, s35
	s_cselect_b32 s27, s40, s34
	s_add_u32 s61, s34, 0x100
	s_addc_u32 s62, s35, 0
	s_add_u32 s42, s42, 0x80080
	v_mov_b32_e32 v0, 0
	s_addc_u32 s43, s43, 0
	s_mov_b32 s63, -2
	v_mov_b32_e32 v1, v0
	v_mov_b32_e32 v2, v0
	v_mov_b32_e32 v3, v0
	v_mov_b32_e32 v4, v0
	v_mov_b32_e32 v5, v0
	v_mov_b32_e32 v6, v0
	v_mov_b32_e32 v7, v0
	v_mov_b32_e32 v8, v0
	v_mov_b32_e32 v9, v0
	v_mov_b32_e32 v10, v0
	v_mov_b32_e32 v11, v0
	v_mov_b32_e32 v18, v0
	v_mov_b32_e32 v19, v0
	v_mov_b32_e32 v20, v0
	v_mov_b32_e32 v21, v0
	v_mov_b32_e32 v26, v0
	v_mov_b32_e32 v27, v0
	v_mov_b32_e32 v28, v0
	v_mov_b32_e32 v29, v0
	v_mov_b32_e32 v34, v0
	v_mov_b32_e32 v35, v0
	v_mov_b32_e32 v36, v0
	v_mov_b32_e32 v37, v0
	v_mov_b32_e32 v42, v0
	v_mov_b32_e32 v43, v0
	v_mov_b32_e32 v44, v0
	v_mov_b32_e32 v45, v0
	v_mov_b32_e32 v50, v0
	v_mov_b32_e32 v51, v0
	v_mov_b32_e32 v52, v0
	v_mov_b32_e32 v53, v0
	v_mov_b32_e32 v12, v0
	v_mov_b32_e32 v13, v0
	v_mov_b32_e32 v14, v0
	v_mov_b32_e32 v15, v0
	v_mov_b32_e32 v22, v0
	v_mov_b32_e32 v23, v0
	v_mov_b32_e32 v24, v0
	v_mov_b32_e32 v25, v0
	v_mov_b32_e32 v30, v0
	v_mov_b32_e32 v31, v0
	v_mov_b32_e32 v32, v0
	v_mov_b32_e32 v33, v0
	v_mov_b32_e32 v38, v0
	v_mov_b32_e32 v39, v0
	v_mov_b32_e32 v40, v0
	v_mov_b32_e32 v41, v0
	v_mov_b32_e32 v46, v0
	v_mov_b32_e32 v47, v0
	v_mov_b32_e32 v48, v0
	v_mov_b32_e32 v49, v0
	v_mov_b32_e32 v54, v0
	v_mov_b32_e32 v55, v0
	v_mov_b32_e32 v56, v0
	v_mov_b32_e32 v57, v0
	v_mov_b32_e32 v58, v0
	v_mov_b32_e32 v59, v0
	v_mov_b32_e32 v60, v0
	v_mov_b32_e32 v61, v0
	v_mov_b32_e32 v62, v0
	v_mov_b32_e32 v63, v0
	v_mov_b32_e32 v64, v0
	v_mov_b32_e32 v65, v0
	v_mov_b32_e32 v66, v0
	v_mov_b32_e32 v67, v0
	v_mov_b32_e32 v68, v0
	v_mov_b32_e32 v69, v0
	v_mov_b32_e32 v70, v0
	v_mov_b32_e32 v71, v0
	v_mov_b32_e32 v72, v0
	v_mov_b32_e32 v73, v0
	v_mov_b32_e32 v74, v0
	v_mov_b32_e32 v75, v0
	v_mov_b32_e32 v76, v0
	v_mov_b32_e32 v77, v0
	v_mov_b32_e32 v82, v0
	v_mov_b32_e32 v83, v0
	v_mov_b32_e32 v84, v0
	v_mov_b32_e32 v85, v0
	v_mov_b32_e32 v90, v0
	v_mov_b32_e32 v91, v0
	v_mov_b32_e32 v92, v0
	v_mov_b32_e32 v93, v0
	v_mov_b32_e32 v98, v0
	v_mov_b32_e32 v99, v0
	v_mov_b32_e32 v100, v0
	v_mov_b32_e32 v101, v0
	v_mov_b32_e32 v106, v0
	v_mov_b32_e32 v107, v0
	v_mov_b32_e32 v108, v0
	v_mov_b32_e32 v109, v0
	v_mov_b32_e32 v114, v0
	v_mov_b32_e32 v115, v0
	v_mov_b32_e32 v116, v0
	v_mov_b32_e32 v117, v0
	v_mov_b32_e32 v78, v0
	v_mov_b32_e32 v79, v0
	v_mov_b32_e32 v80, v0
	v_mov_b32_e32 v81, v0
	v_mov_b32_e32 v86, v0
	v_mov_b32_e32 v87, v0
	v_mov_b32_e32 v88, v0
	v_mov_b32_e32 v89, v0
	v_mov_b32_e32 v94, v0
	v_mov_b32_e32 v95, v0
	v_mov_b32_e32 v96, v0
	v_mov_b32_e32 v97, v0
	v_mov_b32_e32 v102, v0
	v_mov_b32_e32 v103, v0
	v_mov_b32_e32 v104, v0
	v_mov_b32_e32 v105, v0
	v_mov_b32_e32 v110, v0
	v_mov_b32_e32 v111, v0
	v_mov_b32_e32 v112, v0
	v_mov_b32_e32 v113, v0
	v_mov_b32_e32 v118, v0
	v_mov_b32_e32 v119, v0
	v_mov_b32_e32 v120, v0
	v_mov_b32_e32 v121, v0
	v_mov_b32_e32 v122, v0
	v_mov_b32_e32 v123, v0
	v_mov_b32_e32 v124, v0
	v_mov_b32_e32 v125, v0
	v_mov_b32_e32 v126, v0
	v_mov_b32_e32 v127, v0
	v_mov_b32_e32 v128, v0
	v_mov_b32_e32 v129, v0
	s_and_b64 vcc, exec, s[20:21]
	s_cbranch_vccnz .Lprio_skip_2
	s_setprio 1
.Lprio_skip_2:
.LBB0_430:
	s_add_u32 s34, s42, 0xfff80080
	s_addc_u32 s35, s43, -1
	s_add_i32 s64, 0, 0x10000
	s_cmp_eq_u32 s63, 28
	s_cselect_b32 s47, s4, s35
	s_cselect_b32 s46, s5, s34
	v_add_u32_e32 v149, s64, v146
	s_cselect_b32 s35, s23, s62
	s_cselect_b32 s34, s27, s61
	s_add_i32 s66, 0, 0x14000
	ds_read_b128 v[142:145], v149
	ds_read_b128 v[160:163], v149 offset:1024
	ds_read_b128 v[164:167], v149 offset:2048
	ds_read_b128 v[168:171], v149 offset:3072
	v_add_u32_e32 v149, s66, v146
	ds_read_b128 v[172:175], v149
	ds_read_b128 v[176:179], v149 offset:1024
	ds_read_b128 v[180:183], v149 offset:2048
	ds_read_b128 v[212:215], v149 offset:3072
	v_lshl_add_u64 v[150:151], s[42:43], 0, v[140:141]
	s_add_i32 m0, s31, 0xc000
	ds_read_b128 v[216:219], v148
	ds_read_b128 v[220:223], v148 offset:1024
	ds_read_b128 v[224:227], v148 offset:2048
	ds_read_b128 v[228:231], v148 offset:3072
	ds_read_b128 v[232:235], v148 offset:4096
	ds_read_b128 v[236:239], v148 offset:5120
	ds_read_b128 v[240:243], v148 offset:6144
	ds_read_b128 v[244:247], v148 offset:7168
	global_load_lds_dwordx4 v[150:151], off
	v_lshl_add_u64 v[150:151], s[42:43], 0, v[138:139]
	s_add_i32 m0, s31, 0xe000
	s_nop 0
	global_load_lds_dwordx4 v[150:151], off
	s_waitcnt vmcnt(8)
	s_waitcnt lgkmcnt(0)
	s_barrier
	s_waitcnt lgkmcnt(0)
	v_mfma_f32_16x16x32_bf16 v[126:129], v[142:145], v[216:219], v[126:129]
	v_mfma_f32_16x16x32_bf16 v[122:125], v[164:167], v[216:219], v[122:125]
	v_mfma_f32_16x16x32_bf16 v[118:121], v[142:145], v[224:227], v[118:121]
	v_mfma_f32_16x16x32_bf16 v[110:113], v[164:167], v[224:227], v[110:113]
	v_mfma_f32_16x16x32_bf16 v[102:105], v[142:145], v[232:235], v[102:105]
	v_mfma_f32_16x16x32_bf16 v[94:97], v[164:167], v[232:235], v[94:97]
	v_mfma_f32_16x16x32_bf16 v[86:89], v[142:145], v[240:243], v[86:89]
	v_mfma_f32_16x16x32_bf16 v[78:81], v[164:167], v[240:243], v[78:81]
	v_mfma_f32_16x16x32_bf16 v[126:129], v[160:163], v[220:223], v[126:129]
	v_mfma_f32_16x16x32_bf16 v[122:125], v[168:171], v[220:223], v[122:125]
	v_mfma_f32_16x16x32_bf16 v[118:121], v[160:163], v[228:231], v[118:121]
	v_mfma_f32_16x16x32_bf16 v[110:113], v[168:171], v[228:231], v[110:113]
	v_mfma_f32_16x16x32_bf16 v[102:105], v[160:163], v[236:239], v[102:105]
	v_mfma_f32_16x16x32_bf16 v[94:97], v[168:171], v[236:239], v[94:97]
	v_mfma_f32_16x16x32_bf16 v[86:89], v[160:163], v[244:247], v[86:89]
	v_mfma_f32_16x16x32_bf16 v[78:81], v[168:171], v[244:247], v[78:81]
	v_mfma_f32_16x16x32_bf16 v[114:117], v[172:175], v[216:219], v[114:117]
	v_mfma_f32_16x16x32_bf16 v[106:109], v[180:183], v[216:219], v[106:109]
	v_mfma_f32_16x16x32_bf16 v[98:101], v[172:175], v[224:227], v[98:101]
	v_mfma_f32_16x16x32_bf16 v[90:93], v[180:183], v[224:227], v[90:93]
	v_mfma_f32_16x16x32_bf16 v[82:85], v[172:175], v[232:235], v[82:85]
	v_mfma_f32_16x16x32_bf16 v[74:77], v[180:183], v[232:235], v[74:77]
	v_mfma_f32_16x16x32_bf16 v[70:73], v[172:175], v[240:243], v[70:73]
	v_mfma_f32_16x16x32_bf16 v[66:69], v[180:183], v[240:243], v[66:69]
	v_mfma_f32_16x16x32_bf16 v[114:117], v[176:179], v[220:223], v[114:117]
	v_mfma_f32_16x16x32_bf16 v[106:109], v[212:215], v[220:223], v[106:109]
	v_mfma_f32_16x16x32_bf16 v[98:101], v[176:179], v[228:231], v[98:101]
	v_mfma_f32_16x16x32_bf16 v[90:93], v[212:215], v[228:231], v[90:93]
	v_mfma_f32_16x16x32_bf16 v[82:85], v[176:179], v[236:239], v[82:85]
	v_mfma_f32_16x16x32_bf16 v[74:77], v[212:215], v[236:239], v[74:77]
	v_mfma_f32_16x16x32_bf16 v[70:73], v[176:179], v[244:247], v[70:73]
	v_mfma_f32_16x16x32_bf16 v[66:69], v[212:215], v[244:247], v[66:69]
	s_barrier
	s_add_i32 s64, s64, s51
	v_lshl_add_u64 v[150:151], s[34:35], 0, v[134:135]
	s_mov_b32 m0, s64
	ds_read_b128 v[216:219], v148 offset:16384
	ds_read_b128 v[220:223], v148 offset:17408
	ds_read_b128 v[224:227], v148 offset:18432
	ds_read_b128 v[228:231], v148 offset:19456
	ds_read_b128 v[232:235], v148 offset:20480
	ds_read_b128 v[236:239], v148 offset:21504
	ds_read_b128 v[240:243], v148 offset:22528
	ds_read_b128 v[244:247], v148 offset:23552
	global_load_lds_dwordx4 v[150:151], off
	s_add_i32 m0, s64, 0x2000
	s_add_u32 s64, s34, 0x80000
	v_lshl_add_u64 v[152:153], s[34:35], 0, v[130:131]
	s_addc_u32 s65, s35, 0
	s_add_i32 s66, s66, s51
	global_load_lds_dwordx4 v[152:153], off
	v_lshl_add_u64 v[210:211], s[64:65], 0, v[134:135]
	s_mov_b32 m0, s66
	v_lshl_add_u64 v[248:249], s[46:47], 0, v[132:133]
	global_load_lds_dwordx4 v[210:211], off
	v_lshl_add_u64 v[210:211], s[64:65], 0, v[130:131]
	s_add_i32 m0, s66, 0x2000
	s_nop 0
	global_load_lds_dwordx4 v[210:211], off
	v_lshl_add_u64 v[210:211], s[46:47], 0, v[136:137]
	s_mov_b32 m0, s31
	s_nop 0
	global_load_lds_dwordx4 v[210:211], off
	s_mov_b32 m0, s53
	s_nop 0
	global_load_lds_dwordx4 v[248:249], off
	s_waitcnt vmcnt(8)
	s_waitcnt lgkmcnt(0)
	s_barrier
	s_waitcnt lgkmcnt(0)
	v_mfma_f32_16x16x32_bf16 v[62:65], v[142:145], v[216:219], v[62:65]
	v_mfma_f32_16x16x32_bf16 v[58:61], v[164:167], v[216:219], v[58:61]
	v_mfma_f32_16x16x32_bf16 v[54:57], v[142:145], v[224:227], v[54:57]
	v_mfma_f32_16x16x32_bf16 v[46:49], v[164:167], v[224:227], v[46:49]
	v_mfma_f32_16x16x32_bf16 v[38:41], v[142:145], v[232:235], v[38:41]
	v_mfma_f32_16x16x32_bf16 v[30:33], v[164:167], v[232:235], v[30:33]
	v_mfma_f32_16x16x32_bf16 v[22:25], v[142:145], v[240:243], v[22:25]
	v_mfma_f32_16x16x32_bf16 v[12:15], v[164:167], v[240:243], v[12:15]
	v_mfma_f32_16x16x32_bf16 v[62:65], v[160:163], v[220:223], v[62:65]
	v_mfma_f32_16x16x32_bf16 v[58:61], v[168:171], v[220:223], v[58:61]
	v_mfma_f32_16x16x32_bf16 v[54:57], v[160:163], v[228:231], v[54:57]
	v_mfma_f32_16x16x32_bf16 v[46:49], v[168:171], v[228:231], v[46:49]
	v_mfma_f32_16x16x32_bf16 v[38:41], v[160:163], v[236:239], v[38:41]
	v_mfma_f32_16x16x32_bf16 v[30:33], v[168:171], v[236:239], v[30:33]
	v_mfma_f32_16x16x32_bf16 v[22:25], v[160:163], v[244:247], v[22:25]
	v_mfma_f32_16x16x32_bf16 v[12:15], v[168:171], v[244:247], v[12:15]
	v_mfma_f32_16x16x32_bf16 v[50:53], v[172:175], v[216:219], v[50:53]
	v_mfma_f32_16x16x32_bf16 v[42:45], v[180:183], v[216:219], v[42:45]
	v_mfma_f32_16x16x32_bf16 v[34:37], v[172:175], v[224:227], v[34:37]
	v_mfma_f32_16x16x32_bf16 v[26:29], v[180:183], v[224:227], v[26:29]
	v_mfma_f32_16x16x32_bf16 v[18:21], v[172:175], v[232:235], v[18:21]
	v_mfma_f32_16x16x32_bf16 v[8:11], v[180:183], v[232:235], v[8:11]
	v_mfma_f32_16x16x32_bf16 v[4:7], v[172:175], v[240:243], v[4:7]
	v_mfma_f32_16x16x32_bf16 v[0:3], v[180:183], v[240:243], v[0:3]
	v_mfma_f32_16x16x32_bf16 v[50:53], v[176:179], v[220:223], v[50:53]
	v_mfma_f32_16x16x32_bf16 v[42:45], v[212:215], v[220:223], v[42:45]
	v_mfma_f32_16x16x32_bf16 v[34:37], v[176:179], v[228:231], v[34:37]
	v_mfma_f32_16x16x32_bf16 v[26:29], v[212:215], v[228:231], v[26:29]
	v_mfma_f32_16x16x32_bf16 v[18:21], v[176:179], v[236:239], v[18:21]
	v_mfma_f32_16x16x32_bf16 v[8:11], v[212:215], v[236:239], v[8:11]
	v_mfma_f32_16x16x32_bf16 v[4:7], v[176:179], v[244:247], v[4:7]
	v_mfma_f32_16x16x32_bf16 v[0:3], v[212:215], v[244:247], v[0:3]
	s_barrier
	s_add_i32 s64, 0, 0x18000
	v_add_u32_e32 v149, s64, v146
	s_add_i32 s65, 0, 0x1c000
	ds_read_b128 v[142:145], v149
	ds_read_b128 v[160:163], v149 offset:1024
	ds_read_b128 v[164:167], v149 offset:2048
	ds_read_b128 v[168:171], v149 offset:3072
	v_add_u32_e32 v149, s65, v146
	ds_read_b128 v[172:175], v149
	ds_read_b128 v[176:179], v149 offset:1024
	ds_read_b128 v[180:183], v149 offset:2048
	ds_read_b128 v[212:215], v149 offset:3072
	s_add_u32 s46, s46, 0x80000
	s_addc_u32 s47, s47, 0
	s_mov_b32 m0, s54
	v_lshl_add_u64 v[250:251], s[46:47], 0, v[136:137]
	ds_read_b128 v[216:219], v148 offset:32768
	ds_read_b128 v[220:223], v148 offset:33792
	ds_read_b128 v[224:227], v148 offset:34816
	ds_read_b128 v[228:231], v148 offset:35840
	ds_read_b128 v[232:235], v148 offset:36864
	ds_read_b128 v[236:239], v148 offset:37888
	ds_read_b128 v[240:243], v148 offset:38912
	ds_read_b128 v[244:247], v148 offset:39936
	global_load_lds_dwordx4 v[250:251], off
	v_lshl_add_u64 v[250:251], s[46:47], 0, v[132:133]
	s_mov_b32 m0, s55
	s_nop 0
	global_load_lds_dwordx4 v[250:251], off
	s_waitcnt vmcnt(8)
	s_waitcnt lgkmcnt(0)
	s_barrier
	s_waitcnt lgkmcnt(0)
	v_mfma_f32_16x16x32_bf16 v[126:129], v[142:145], v[216:219], v[126:129]
	v_mfma_f32_16x16x32_bf16 v[122:125], v[164:167], v[216:219], v[122:125]
	v_mfma_f32_16x16x32_bf16 v[118:121], v[142:145], v[224:227], v[118:121]
	v_mfma_f32_16x16x32_bf16 v[110:113], v[164:167], v[224:227], v[110:113]
	v_mfma_f32_16x16x32_bf16 v[102:105], v[142:145], v[232:235], v[102:105]
	v_mfma_f32_16x16x32_bf16 v[94:97], v[164:167], v[232:235], v[94:97]
	v_mfma_f32_16x16x32_bf16 v[86:89], v[142:145], v[240:243], v[86:89]
	v_mfma_f32_16x16x32_bf16 v[78:81], v[164:167], v[240:243], v[78:81]
	v_mfma_f32_16x16x32_bf16 v[126:129], v[160:163], v[220:223], v[126:129]
	v_mfma_f32_16x16x32_bf16 v[122:125], v[168:171], v[220:223], v[122:125]
	v_mfma_f32_16x16x32_bf16 v[118:121], v[160:163], v[228:231], v[118:121]
	v_mfma_f32_16x16x32_bf16 v[110:113], v[168:171], v[228:231], v[110:113]
	v_mfma_f32_16x16x32_bf16 v[102:105], v[160:163], v[236:239], v[102:105]
	v_mfma_f32_16x16x32_bf16 v[94:97], v[168:171], v[236:239], v[94:97]
	v_mfma_f32_16x16x32_bf16 v[86:89], v[160:163], v[244:247], v[86:89]
	v_mfma_f32_16x16x32_bf16 v[78:81], v[168:171], v[244:247], v[78:81]
	v_mfma_f32_16x16x32_bf16 v[114:117], v[172:175], v[216:219], v[114:117]
	v_mfma_f32_16x16x32_bf16 v[106:109], v[180:183], v[216:219], v[106:109]
	v_mfma_f32_16x16x32_bf16 v[98:101], v[172:175], v[224:227], v[98:101]
	v_mfma_f32_16x16x32_bf16 v[90:93], v[180:183], v[224:227], v[90:93]
	v_mfma_f32_16x16x32_bf16 v[82:85], v[172:175], v[232:235], v[82:85]
	v_mfma_f32_16x16x32_bf16 v[74:77], v[180:183], v[232:235], v[74:77]
	v_mfma_f32_16x16x32_bf16 v[70:73], v[172:175], v[240:243], v[70:73]
	v_mfma_f32_16x16x32_bf16 v[66:69], v[180:183], v[240:243], v[66:69]
	v_mfma_f32_16x16x32_bf16 v[114:117], v[176:179], v[220:223], v[114:117]
	v_mfma_f32_16x16x32_bf16 v[106:109], v[212:215], v[220:223], v[106:109]
	v_mfma_f32_16x16x32_bf16 v[98:101], v[176:179], v[228:231], v[98:101]
	v_mfma_f32_16x16x32_bf16 v[90:93], v[212:215], v[228:231], v[90:93]
	v_mfma_f32_16x16x32_bf16 v[82:85], v[176:179], v[236:239], v[82:85]
	v_mfma_f32_16x16x32_bf16 v[74:77], v[212:215], v[236:239], v[74:77]
	v_mfma_f32_16x16x32_bf16 v[70:73], v[176:179], v[244:247], v[70:73]
	v_mfma_f32_16x16x32_bf16 v[66:69], v[212:215], v[244:247], v[66:69]
	s_barrier
	s_add_i32 s46, s64, s51
	v_lshl_add_u64 v[150:151], v[150:151], 0, s[96:97]
	s_mov_b32 m0, s46
	ds_read_b128 v[216:219], v148 offset:49152
	ds_read_b128 v[220:223], v148 offset:50176
	ds_read_b128 v[224:227], v148 offset:51200
	ds_read_b128 v[228:231], v148 offset:52224
	ds_read_b128 v[232:235], v148 offset:53248
	ds_read_b128 v[236:239], v148 offset:54272
	ds_read_b128 v[240:243], v148 offset:55296
	ds_read_b128 v[244:247], v148 offset:56320
	global_load_lds_dwordx4 v[150:151], off
	s_add_i32 m0, s46, 0x2000
	s_add_u32 s34, s34, 0x80080
	v_lshl_add_u64 v[150:151], v[152:153], 0, s[96:97]
	s_addc_u32 s35, s35, 0
	s_add_i32 s46, s65, s51
	global_load_lds_dwordx4 v[150:151], off
	v_lshl_add_u64 v[150:151], s[34:35], 0, v[134:135]
	s_mov_b32 m0, s46
	s_nop 0
	global_load_lds_dwordx4 v[150:151], off
	v_lshl_add_u64 v[150:151], s[34:35], 0, v[130:131]
	s_add_i32 m0, s46, 0x2000
	s_nop 0
	global_load_lds_dwordx4 v[150:151], off
	v_lshl_add_u64 v[150:151], v[210:211], 0, s[96:97]
	s_mov_b32 m0, s56
	s_nop 0
	global_load_lds_dwordx4 v[150:151], off
	v_lshl_add_u64 v[150:151], v[248:249], 0, s[96:97]
	s_mov_b32 m0, s57
	s_nop 0
	global_load_lds_dwordx4 v[150:151], off
	s_waitcnt vmcnt(8)
	s_waitcnt lgkmcnt(0)
	s_barrier
	s_waitcnt lgkmcnt(0)
	v_mfma_f32_16x16x32_bf16 v[62:65], v[142:145], v[216:219], v[62:65]
	v_mfma_f32_16x16x32_bf16 v[58:61], v[164:167], v[216:219], v[58:61]
	v_mfma_f32_16x16x32_bf16 v[54:57], v[142:145], v[224:227], v[54:57]
	v_mfma_f32_16x16x32_bf16 v[46:49], v[164:167], v[224:227], v[46:49]
	v_mfma_f32_16x16x32_bf16 v[38:41], v[142:145], v[232:235], v[38:41]
	v_mfma_f32_16x16x32_bf16 v[30:33], v[164:167], v[232:235], v[30:33]
	v_mfma_f32_16x16x32_bf16 v[22:25], v[142:145], v[240:243], v[22:25]
	v_mfma_f32_16x16x32_bf16 v[12:15], v[164:167], v[240:243], v[12:15]
	v_mfma_f32_16x16x32_bf16 v[62:65], v[160:163], v[220:223], v[62:65]
	v_mfma_f32_16x16x32_bf16 v[58:61], v[168:171], v[220:223], v[58:61]
	v_mfma_f32_16x16x32_bf16 v[54:57], v[160:163], v[228:231], v[54:57]
	v_mfma_f32_16x16x32_bf16 v[46:49], v[168:171], v[228:231], v[46:49]
	v_mfma_f32_16x16x32_bf16 v[38:41], v[160:163], v[236:239], v[38:41]
	v_mfma_f32_16x16x32_bf16 v[30:33], v[168:171], v[236:239], v[30:33]
	v_mfma_f32_16x16x32_bf16 v[22:25], v[160:163], v[244:247], v[22:25]
	v_mfma_f32_16x16x32_bf16 v[12:15], v[168:171], v[244:247], v[12:15]
	v_mfma_f32_16x16x32_bf16 v[50:53], v[172:175], v[216:219], v[50:53]
	v_mfma_f32_16x16x32_bf16 v[42:45], v[180:183], v[216:219], v[42:45]
	v_mfma_f32_16x16x32_bf16 v[34:37], v[172:175], v[224:227], v[34:37]
	v_mfma_f32_16x16x32_bf16 v[26:29], v[180:183], v[224:227], v[26:29]
	v_mfma_f32_16x16x32_bf16 v[18:21], v[172:175], v[232:235], v[18:21]
	v_mfma_f32_16x16x32_bf16 v[8:11], v[180:183], v[232:235], v[8:11]
	v_mfma_f32_16x16x32_bf16 v[4:7], v[172:175], v[240:243], v[4:7]
	v_mfma_f32_16x16x32_bf16 v[0:3], v[180:183], v[240:243], v[0:3]
	v_mfma_f32_16x16x32_bf16 v[50:53], v[176:179], v[220:223], v[50:53]
	v_mfma_f32_16x16x32_bf16 v[42:45], v[212:215], v[220:223], v[42:45]
	v_mfma_f32_16x16x32_bf16 v[34:37], v[176:179], v[228:231], v[34:37]
	v_mfma_f32_16x16x32_bf16 v[26:29], v[212:215], v[228:231], v[26:29]
	v_mfma_f32_16x16x32_bf16 v[18:21], v[176:179], v[236:239], v[18:21]
	v_mfma_f32_16x16x32_bf16 v[8:11], v[212:215], v[236:239], v[8:11]
	v_mfma_f32_16x16x32_bf16 v[4:7], v[176:179], v[244:247], v[4:7]
	v_mfma_f32_16x16x32_bf16 v[0:3], v[212:215], v[244:247], v[0:3]
	s_barrier
	s_add_i32 s63, s63, 2
	s_add_u32 s61, s61, 0x100
	s_addc_u32 s62, s62, 0
	s_add_u32 s42, s42, 0x100
	s_addc_u32 s43, s43, 0
	s_cmp_gt_u32 s63, 29
	s_cbranch_scc0 .LBB0_430
	s_setprio 0
	s_and_b64 vcc, exec, s[20:21]
	s_cbranch_vccz .LBB0_433
	s_barrier

.LBB0_1622:
	s_ashr_i32 s27, s26, 31
	s_lshl_b64 s[4:5], s[26:27], 20
	s_add_u32 s30, s46, s4
	s_addc_u32 s31, s47, s5
	s_and_b64 s[4:5], s[36:37], exec
	s_cselect_b32 s4, s31, s43
	s_cselect_b32 s5, s30, s42
	s_ashr_i32 s23, s22, 31
	s_lshl_b64 s[38:39], s[22:23], 20
	s_add_u32 s38, s48, s38
	s_addc_u32 s39, s49, s39
	s_and_b64 s[44:45], s[36:37], exec
	s_cselect_b32 s23, s39, s35
	s_cselect_b32 s27, s38, s34
	s_add_u32 s61, s34, 0x100
	s_addc_u32 s62, s35, 0
	s_add_u32 s42, s42, 0x80080
	v_mov_b32_e32 v0, 0
	s_addc_u32 s43, s43, 0
	s_mov_b32 s63, -2
	v_mov_b32_e32 v1, v0
	v_mov_b32_e32 v2, v0
	v_mov_b32_e32 v3, v0
	v_mov_b32_e32 v4, v0
	v_mov_b32_e32 v5, v0
	v_mov_b32_e32 v6, v0
	v_mov_b32_e32 v7, v0
	v_mov_b32_e32 v8, v0
	v_mov_b32_e32 v9, v0
	v_mov_b32_e32 v10, v0
	v_mov_b32_e32 v11, v0
	v_mov_b32_e32 v12, v0
	v_mov_b32_e32 v13, v0
	v_mov_b32_e32 v14, v0
	v_mov_b32_e32 v15, v0
	v_mov_b32_e32 v18, v0
	v_mov_b32_e32 v19, v0
	v_mov_b32_e32 v20, v0
	v_mov_b32_e32 v21, v0
	v_mov_b32_e32 v22, v0
	v_mov_b32_e32 v23, v0
	v_mov_b32_e32 v24, v0
	v_mov_b32_e32 v25, v0
	v_mov_b32_e32 v26, v0
	v_mov_b32_e32 v27, v0
	v_mov_b32_e32 v28, v0
	v_mov_b32_e32 v29, v0
	v_mov_b32_e32 v30, v0
	v_mov_b32_e32 v31, v0
	v_mov_b32_e32 v32, v0
	v_mov_b32_e32 v33, v0
	v_mov_b32_e32 v58, v0
	v_mov_b32_e32 v59, v0
	v_mov_b32_e32 v60, v0
	v_mov_b32_e32 v61, v0
	v_mov_b32_e32 v66, v0
	v_mov_b32_e32 v67, v0
	v_mov_b32_e32 v68, v0
	v_mov_b32_e32 v69, v0
	v_mov_b32_e32 v74, v0
	v_mov_b32_e32 v75, v0
	v_mov_b32_e32 v76, v0
	v_mov_b32_e32 v77, v0
	v_mov_b32_e32 v78, v0
	v_mov_b32_e32 v79, v0
	v_mov_b32_e32 v80, v0
	v_mov_b32_e32 v81, v0
	v_mov_b32_e32 v82, v0
	v_mov_b32_e32 v83, v0
	v_mov_b32_e32 v84, v0
	v_mov_b32_e32 v85, v0
	v_mov_b32_e32 v86, v0
	v_mov_b32_e32 v87, v0
	v_mov_b32_e32 v88, v0
	v_mov_b32_e32 v89, v0
	v_mov_b32_e32 v90, v0
	v_mov_b32_e32 v91, v0
	v_mov_b32_e32 v92, v0
	v_mov_b32_e32 v93, v0
	v_mov_b32_e32 v94, v0
	v_mov_b32_e32 v95, v0
	v_mov_b32_e32 v96, v0
	v_mov_b32_e32 v97, v0
	v_mov_b32_e32 v34, v0
	v_mov_b32_e32 v35, v0
	v_mov_b32_e32 v36, v0
	v_mov_b32_e32 v37, v0
	v_mov_b32_e32 v38, v0
	v_mov_b32_e32 v39, v0
	v_mov_b32_e32 v40, v0
	v_mov_b32_e32 v41, v0
	v_mov_b32_e32 v42, v0
	v_mov_b32_e32 v43, v0
	v_mov_b32_e32 v44, v0
	v_mov_b32_e32 v45, v0
	v_mov_b32_e32 v46, v0
	v_mov_b32_e32 v47, v0
	v_mov_b32_e32 v48, v0
	v_mov_b32_e32 v49, v0
	v_mov_b32_e32 v50, v0
	v_mov_b32_e32 v51, v0
	v_mov_b32_e32 v52, v0
	v_mov_b32_e32 v53, v0
	v_mov_b32_e32 v54, v0
	v_mov_b32_e32 v55, v0
	v_mov_b32_e32 v56, v0
	v_mov_b32_e32 v57, v0
	v_mov_b32_e32 v62, v0
	v_mov_b32_e32 v63, v0
	v_mov_b32_e32 v64, v0
	v_mov_b32_e32 v65, v0
	v_mov_b32_e32 v70, v0
	v_mov_b32_e32 v71, v0
	v_mov_b32_e32 v72, v0
	v_mov_b32_e32 v73, v0
	v_mov_b32_e32 v98, v0
	v_mov_b32_e32 v99, v0
	v_mov_b32_e32 v100, v0
	v_mov_b32_e32 v101, v0
	v_mov_b32_e32 v102, v0
	v_mov_b32_e32 v103, v0
	v_mov_b32_e32 v104, v0
	v_mov_b32_e32 v105, v0
	v_mov_b32_e32 v106, v0
	v_mov_b32_e32 v107, v0
	v_mov_b32_e32 v108, v0
	v_mov_b32_e32 v109, v0
	v_mov_b32_e32 v110, v0
	v_mov_b32_e32 v111, v0
	v_mov_b32_e32 v112, v0
	v_mov_b32_e32 v113, v0
	v_mov_b32_e32 v114, v0
	v_mov_b32_e32 v115, v0
	v_mov_b32_e32 v116, v0
	v_mov_b32_e32 v117, v0
	v_mov_b32_e32 v118, v0
	v_mov_b32_e32 v119, v0
	v_mov_b32_e32 v120, v0
	v_mov_b32_e32 v121, v0
	v_mov_b32_e32 v130, v0
	v_mov_b32_e32 v131, v0
	v_mov_b32_e32 v132, v0
	v_mov_b32_e32 v133, v0
	v_mov_b32_e32 v134, v0
	v_mov_b32_e32 v135, v0
	v_mov_b32_e32 v136, v0
	v_mov_b32_e32 v137, v0
	s_and_b64 vcc, exec, s[20:21]
	s_cbranch_vccnz .Lprio_skip_3
	s_setprio 1
.Lprio_skip_3:
.LBB0_1623:
	s_add_u32 s34, s42, 0xfff80080
	s_addc_u32 s35, s43, -1
	s_add_i32 s64, 0, 0x10000
	s_cmp_eq_u32 s63, 28
	s_cselect_b32 s45, s4, s35
	s_cselect_b32 s44, s5, s34
	v_add_u32_e32 v150, s64, v166
	s_cselect_b32 s35, s23, s62
	s_cselect_b32 s34, s27, s61
	s_add_i32 s66, 0, 0x14000
	ds_read_b128 v[122:125], v150
	ds_read_b128 v[126:129], v150 offset:1024
	ds_read_b128 v[160:163], v150 offset:2048
	ds_read_b128 v[170:173], v150 offset:3072
	v_add_u32_e32 v150, s66, v166
	ds_read_b128 v[174:177], v150
	ds_read_b128 v[178:181], v150 offset:1024
	ds_read_b128 v[212:215], v150 offset:2048
	ds_read_b128 v[216:219], v150 offset:3072
	v_lshl_add_u64 v[150:151], s[42:43], 0, v[148:149]
	s_add_i32 m0, s41, 0xc000
	ds_read_b128 v[220:223], v168
	ds_read_b128 v[224:227], v168 offset:1024
	ds_read_b128 v[228:231], v168 offset:2048
	ds_read_b128 v[232:235], v168 offset:3072
	ds_read_b128 v[236:239], v168 offset:4096
	ds_read_b128 v[240:243], v168 offset:5120
	ds_read_b128 v[244:247], v168 offset:6144
	ds_read_b128 v[248:251], v168 offset:7168
	global_load_lds_dwordx4 v[150:151], off
	v_lshl_add_u64 v[150:151], s[42:43], 0, v[146:147]
	s_add_i32 m0, s41, 0xe000
	s_nop 0
	global_load_lds_dwordx4 v[150:151], off
	s_waitcnt vmcnt(8)
	s_waitcnt lgkmcnt(0)
	s_barrier
	s_waitcnt lgkmcnt(0)
	v_mfma_f32_16x16x32_bf16 v[134:137], v[122:125], v[220:223], v[134:137]
	v_mfma_f32_16x16x32_bf16 v[130:133], v[160:163], v[220:223], v[130:133]
	v_mfma_f32_16x16x32_bf16 v[118:121], v[122:125], v[228:231], v[118:121]
	v_mfma_f32_16x16x32_bf16 v[114:117], v[160:163], v[228:231], v[114:117]
	v_mfma_f32_16x16x32_bf16 v[110:113], v[122:125], v[236:239], v[110:113]
	v_mfma_f32_16x16x32_bf16 v[106:109], v[160:163], v[236:239], v[106:109]
	v_mfma_f32_16x16x32_bf16 v[102:105], v[122:125], v[244:247], v[102:105]
	v_mfma_f32_16x16x32_bf16 v[98:101], v[160:163], v[244:247], v[98:101]
	v_mfma_f32_16x16x32_bf16 v[134:137], v[126:129], v[224:227], v[134:137]
	v_mfma_f32_16x16x32_bf16 v[130:133], v[170:173], v[224:227], v[130:133]
	v_mfma_f32_16x16x32_bf16 v[118:121], v[126:129], v[232:235], v[118:121]
	v_mfma_f32_16x16x32_bf16 v[114:117], v[170:173], v[232:235], v[114:117]
	v_mfma_f32_16x16x32_bf16 v[110:113], v[126:129], v[240:243], v[110:113]
	v_mfma_f32_16x16x32_bf16 v[106:109], v[170:173], v[240:243], v[106:109]
	v_mfma_f32_16x16x32_bf16 v[102:105], v[126:129], v[248:251], v[102:105]
	v_mfma_f32_16x16x32_bf16 v[98:101], v[170:173], v[248:251], v[98:101]
	v_mfma_f32_16x16x32_bf16 v[70:73], v[174:177], v[220:223], v[70:73]
	v_mfma_f32_16x16x32_bf16 v[62:65], v[212:215], v[220:223], v[62:65]
	v_mfma_f32_16x16x32_bf16 v[54:57], v[174:177], v[228:231], v[54:57]
	v_mfma_f32_16x16x32_bf16 v[50:53], v[212:215], v[228:231], v[50:53]
	v_mfma_f32_16x16x32_bf16 v[46:49], v[174:177], v[236:239], v[46:49]
	v_mfma_f32_16x16x32_bf16 v[42:45], v[212:215], v[236:239], v[42:45]
	v_mfma_f32_16x16x32_bf16 v[38:41], v[174:177], v[244:247], v[38:41]
	v_mfma_f32_16x16x32_bf16 v[34:37], v[212:215], v[244:247], v[34:37]
	v_mfma_f32_16x16x32_bf16 v[70:73], v[178:181], v[224:227], v[70:73]
	v_mfma_f32_16x16x32_bf16 v[62:65], v[216:219], v[224:227], v[62:65]
	v_mfma_f32_16x16x32_bf16 v[54:57], v[178:181], v[232:235], v[54:57]
	v_mfma_f32_16x16x32_bf16 v[50:53], v[216:219], v[232:235], v[50:53]
	v_mfma_f32_16x16x32_bf16 v[46:49], v[178:181], v[240:243], v[46:49]
	v_mfma_f32_16x16x32_bf16 v[42:45], v[216:219], v[240:243], v[42:45]
	v_mfma_f32_16x16x32_bf16 v[38:41], v[178:181], v[248:251], v[38:41]
	v_mfma_f32_16x16x32_bf16 v[34:37], v[216:219], v[248:251], v[34:37]
	s_barrier
	s_add_i32 s64, s64, s50
	v_lshl_add_u64 v[150:151], s[34:35], 0, v[140:141]
	s_mov_b32 m0, s64
	ds_read_b128 v[220:223], v168 offset:16384
	ds_read_b128 v[224:227], v168 offset:17408
	ds_read_b128 v[228:231], v168 offset:18432
	ds_read_b128 v[232:235], v168 offset:19456
	ds_read_b128 v[236:239], v168 offset:20480
	ds_read_b128 v[240:243], v168 offset:21504
	ds_read_b128 v[244:247], v168 offset:22528
	ds_read_b128 v[248:251], v168 offset:23552
	global_load_lds_dwordx4 v[150:151], off
	s_add_i32 m0, s64, 0x2000
	s_add_u32 s64, s34, 0x80000
	v_lshl_add_u64 v[152:153], s[34:35], 0, v[144:145]
	s_addc_u32 s65, s35, 0
	s_add_i32 s66, s66, s50
	global_load_lds_dwordx4 v[152:153], off
	v_lshl_add_u64 v[164:165], s[64:65], 0, v[140:141]
	s_mov_b32 m0, s66
	v_lshl_add_u64 v[182:183], s[44:45], 0, v[142:143]
	global_load_lds_dwordx4 v[164:165], off
	v_lshl_add_u64 v[164:165], s[64:65], 0, v[144:145]
	s_add_i32 m0, s66, 0x2000
	s_nop 0
	global_load_lds_dwordx4 v[164:165], off
	v_lshl_add_u64 v[164:165], s[44:45], 0, v[138:139]
	s_mov_b32 m0, s41
	s_nop 0
	global_load_lds_dwordx4 v[164:165], off
	s_mov_b32 m0, s51
	s_nop 0
	global_load_lds_dwordx4 v[182:183], off
	s_waitcnt vmcnt(8)
	s_waitcnt lgkmcnt(0)
	s_barrier
	s_waitcnt lgkmcnt(0)
	v_mfma_f32_16x16x32_bf16 v[94:97], v[122:125], v[220:223], v[94:97]
	v_mfma_f32_16x16x32_bf16 v[90:93], v[160:163], v[220:223], v[90:93]
	v_mfma_f32_16x16x32_bf16 v[86:89], v[122:125], v[228:231], v[86:89]
	v_mfma_f32_16x16x32_bf16 v[82:85], v[160:163], v[228:231], v[82:85]
	v_mfma_f32_16x16x32_bf16 v[78:81], v[122:125], v[236:239], v[78:81]
	v_mfma_f32_16x16x32_bf16 v[74:77], v[160:163], v[236:239], v[74:77]
	v_mfma_f32_16x16x32_bf16 v[66:69], v[122:125], v[244:247], v[66:69]
	v_mfma_f32_16x16x32_bf16 v[58:61], v[160:163], v[244:247], v[58:61]
	v_mfma_f32_16x16x32_bf16 v[94:97], v[126:129], v[224:227], v[94:97]
	v_mfma_f32_16x16x32_bf16 v[90:93], v[170:173], v[224:227], v[90:93]
	v_mfma_f32_16x16x32_bf16 v[86:89], v[126:129], v[232:235], v[86:89]
	v_mfma_f32_16x16x32_bf16 v[82:85], v[170:173], v[232:235], v[82:85]
	v_mfma_f32_16x16x32_bf16 v[78:81], v[126:129], v[240:243], v[78:81]
	v_mfma_f32_16x16x32_bf16 v[74:77], v[170:173], v[240:243], v[74:77]
	v_mfma_f32_16x16x32_bf16 v[66:69], v[126:129], v[248:251], v[66:69]
	v_mfma_f32_16x16x32_bf16 v[58:61], v[170:173], v[248:251], v[58:61]
	v_mfma_f32_16x16x32_bf16 v[30:33], v[174:177], v[220:223], v[30:33]
	v_mfma_f32_16x16x32_bf16 v[26:29], v[212:215], v[220:223], v[26:29]
	v_mfma_f32_16x16x32_bf16 v[22:25], v[174:177], v[228:231], v[22:25]
	v_mfma_f32_16x16x32_bf16 v[18:21], v[212:215], v[228:231], v[18:21]
	v_mfma_f32_16x16x32_bf16 v[12:15], v[174:177], v[236:239], v[12:15]
	v_mfma_f32_16x16x32_bf16 v[8:11], v[212:215], v[236:239], v[8:11]
	v_mfma_f32_16x16x32_bf16 v[4:7], v[174:177], v[244:247], v[4:7]
	v_mfma_f32_16x16x32_bf16 v[0:3], v[212:215], v[244:247], v[0:3]
	v_mfma_f32_16x16x32_bf16 v[30:33], v[178:181], v[224:227], v[30:33]
	v_mfma_f32_16x16x32_bf16 v[26:29], v[216:219], v[224:227], v[26:29]
	v_mfma_f32_16x16x32_bf16 v[22:25], v[178:181], v[232:235], v[22:25]
	v_mfma_f32_16x16x32_bf16 v[18:21], v[216:219], v[232:235], v[18:21]
	v_mfma_f32_16x16x32_bf16 v[12:15], v[178:181], v[240:243], v[12:15]
	v_mfma_f32_16x16x32_bf16 v[8:11], v[216:219], v[240:243], v[8:11]
	v_mfma_f32_16x16x32_bf16 v[4:7], v[178:181], v[248:251], v[4:7]
	v_mfma_f32_16x16x32_bf16 v[0:3], v[216:219], v[248:251], v[0:3]
	s_barrier
	s_add_i32 s64, 0, 0x18000
	v_add_u32_e32 v169, s64, v166
	s_add_i32 s65, 0, 0x1c000
	ds_read_b128 v[122:125], v169
	ds_read_b128 v[126:129], v169 offset:1024
	ds_read_b128 v[160:163], v169 offset:2048
	ds_read_b128 v[170:173], v169 offset:3072
	v_add_u32_e32 v169, s65, v166
	ds_read_b128 v[174:177], v169
	ds_read_b128 v[178:181], v169 offset:1024
	ds_read_b128 v[212:215], v169 offset:2048
	ds_read_b128 v[216:219], v169 offset:3072
	s_add_u32 s44, s44, 0x80000
	s_addc_u32 s45, s45, 0
	s_mov_b32 m0, s52
	v_lshl_add_u64 v[210:211], s[44:45], 0, v[138:139]
	ds_read_b128 v[220:223], v168 offset:32768
	ds_read_b128 v[224:227], v168 offset:33792
	ds_read_b128 v[228:231], v168 offset:34816
	ds_read_b128 v[232:235], v168 offset:35840
	ds_read_b128 v[236:239], v168 offset:36864
	ds_read_b128 v[240:243], v168 offset:37888
	ds_read_b128 v[244:247], v168 offset:38912
	ds_read_b128 v[248:251], v168 offset:39936
	global_load_lds_dwordx4 v[210:211], off
	v_lshl_add_u64 v[210:211], s[44:45], 0, v[142:143]
	s_mov_b32 m0, s53
	s_nop 0
	global_load_lds_dwordx4 v[210:211], off
	s_waitcnt vmcnt(8)
	s_waitcnt lgkmcnt(0)
	s_barrier
	s_waitcnt lgkmcnt(0)
	v_mfma_f32_16x16x32_bf16 v[134:137], v[122:125], v[220:223], v[134:137]
	v_mfma_f32_16x16x32_bf16 v[130:133], v[160:163], v[220:223], v[130:133]
	v_mfma_f32_16x16x32_bf16 v[118:121], v[122:125], v[228:231], v[118:121]
	v_mfma_f32_16x16x32_bf16 v[114:117], v[160:163], v[228:231], v[114:117]
	v_mfma_f32_16x16x32_bf16 v[110:113], v[122:125], v[236:239], v[110:113]
	v_mfma_f32_16x16x32_bf16 v[106:109], v[160:163], v[236:239], v[106:109]
	v_mfma_f32_16x16x32_bf16 v[102:105], v[122:125], v[244:247], v[102:105]
	v_mfma_f32_16x16x32_bf16 v[98:101], v[160:163], v[244:247], v[98:101]
	v_mfma_f32_16x16x32_bf16 v[134:137], v[126:129], v[224:227], v[134:137]
	v_mfma_f32_16x16x32_bf16 v[130:133], v[170:173], v[224:227], v[130:133]
	v_mfma_f32_16x16x32_bf16 v[118:121], v[126:129], v[232:235], v[118:121]
	v_mfma_f32_16x16x32_bf16 v[114:117], v[170:173], v[232:235], v[114:117]
	v_mfma_f32_16x16x32_bf16 v[110:113], v[126:129], v[240:243], v[110:113]
	v_mfma_f32_16x16x32_bf16 v[106:109], v[170:173], v[240:243], v[106:109]
	v_mfma_f32_16x16x32_bf16 v[102:105], v[126:129], v[248:251], v[102:105]
	v_mfma_f32_16x16x32_bf16 v[98:101], v[170:173], v[248:251], v[98:101]
	v_mfma_f32_16x16x32_bf16 v[70:73], v[174:177], v[220:223], v[70:73]
	v_mfma_f32_16x16x32_bf16 v[62:65], v[212:215], v[220:223], v[62:65]
	v_mfma_f32_16x16x32_bf16 v[54:57], v[174:177], v[228:231], v[54:57]
	v_mfma_f32_16x16x32_bf16 v[50:53], v[212:215], v[228:231], v[50:53]
	v_mfma_f32_16x16x32_bf16 v[46:49], v[174:177], v[236:239], v[46:49]
	v_mfma_f32_16x16x32_bf16 v[42:45], v[212:215], v[236:239], v[42:45]
	v_mfma_f32_16x16x32_bf16 v[38:41], v[174:177], v[244:247], v[38:41]
	v_mfma_f32_16x16x32_bf16 v[34:37], v[212:215], v[244:247], v[34:37]
	v_mfma_f32_16x16x32_bf16 v[70:73], v[178:181], v[224:227], v[70:73]
	v_mfma_f32_16x16x32_bf16 v[62:65], v[216:219], v[224:227], v[62:65]
	v_mfma_f32_16x16x32_bf16 v[54:57], v[178:181], v[232:235], v[54:57]
	v_mfma_f32_16x16x32_bf16 v[50:53], v[216:219], v[232:235], v[50:53]
	v_mfma_f32_16x16x32_bf16 v[46:49], v[178:181], v[240:243], v[46:49]
	v_mfma_f32_16x16x32_bf16 v[42:45], v[216:219], v[240:243], v[42:45]
	v_mfma_f32_16x16x32_bf16 v[38:41], v[178:181], v[248:251], v[38:41]
	v_mfma_f32_16x16x32_bf16 v[34:37], v[216:219], v[248:251], v[34:37]
	s_barrier
	s_add_i32 s44, s64, s50
	v_lshl_add_u64 v[150:151], v[150:151], 0, s[96:97]
	s_mov_b32 m0, s44
	ds_read_b128 v[220:223], v168 offset:49152
	ds_read_b128 v[224:227], v168 offset:50176
	ds_read_b128 v[228:231], v168 offset:51200
	ds_read_b128 v[232:235], v168 offset:52224
	ds_read_b128 v[236:239], v168 offset:53248
	ds_read_b128 v[240:243], v168 offset:54272
	ds_read_b128 v[244:247], v168 offset:55296
	ds_read_b128 v[248:251], v168 offset:56320
	global_load_lds_dwordx4 v[150:151], off
	s_add_i32 m0, s44, 0x2000
	s_add_u32 s34, s34, 0x80080
	v_lshl_add_u64 v[150:151], v[152:153], 0, s[96:97]
	s_addc_u32 s35, s35, 0
	s_add_i32 s44, s65, s50
	global_load_lds_dwordx4 v[150:151], off
	v_lshl_add_u64 v[150:151], s[34:35], 0, v[140:141]
	s_mov_b32 m0, s44
	s_nop 0
	global_load_lds_dwordx4 v[150:151], off
	v_lshl_add_u64 v[150:151], s[34:35], 0, v[144:145]
	s_add_i32 m0, s44, 0x2000
	s_nop 0
	global_load_lds_dwordx4 v[150:151], off
	v_lshl_add_u64 v[150:151], v[164:165], 0, s[96:97]
	s_mov_b32 m0, s56
	s_nop 0
	global_load_lds_dwordx4 v[150:151], off
	v_lshl_add_u64 v[150:151], v[182:183], 0, s[96:97]
	s_mov_b32 m0, s57
	s_nop 0
	global_load_lds_dwordx4 v[150:151], off
	s_waitcnt vmcnt(8)
	s_waitcnt lgkmcnt(0)
	s_barrier
	s_waitcnt lgkmcnt(0)
	v_mfma_f32_16x16x32_bf16 v[94:97], v[122:125], v[220:223], v[94:97]
	v_mfma_f32_16x16x32_bf16 v[90:93], v[160:163], v[220:223], v[90:93]
	v_mfma_f32_16x16x32_bf16 v[86:89], v[122:125], v[228:231], v[86:89]
	v_mfma_f32_16x16x32_bf16 v[82:85], v[160:163], v[228:231], v[82:85]
	v_mfma_f32_16x16x32_bf16 v[78:81], v[122:125], v[236:239], v[78:81]
	v_mfma_f32_16x16x32_bf16 v[74:77], v[160:163], v[236:239], v[74:77]
	v_mfma_f32_16x16x32_bf16 v[66:69], v[122:125], v[244:247], v[66:69]
	v_mfma_f32_16x16x32_bf16 v[58:61], v[160:163], v[244:247], v[58:61]
	v_mfma_f32_16x16x32_bf16 v[94:97], v[126:129], v[224:227], v[94:97]
	v_mfma_f32_16x16x32_bf16 v[90:93], v[170:173], v[224:227], v[90:93]
	v_mfma_f32_16x16x32_bf16 v[86:89], v[126:129], v[232:235], v[86:89]
	v_mfma_f32_16x16x32_bf16 v[82:85], v[170:173], v[232:235], v[82:85]
	v_mfma_f32_16x16x32_bf16 v[78:81], v[126:129], v[240:243], v[78:81]
	v_mfma_f32_16x16x32_bf16 v[74:77], v[170:173], v[240:243], v[74:77]
	v_mfma_f32_16x16x32_bf16 v[66:69], v[126:129], v[248:251], v[66:69]
	v_mfma_f32_16x16x32_bf16 v[58:61], v[170:173], v[248:251], v[58:61]
	v_mfma_f32_16x16x32_bf16 v[30:33], v[174:177], v[220:223], v[30:33]
	v_mfma_f32_16x16x32_bf16 v[26:29], v[212:215], v[220:223], v[26:29]
	v_mfma_f32_16x16x32_bf16 v[22:25], v[174:177], v[228:231], v[22:25]
	v_mfma_f32_16x16x32_bf16 v[18:21], v[212:215], v[228:231], v[18:21]
	v_mfma_f32_16x16x32_bf16 v[12:15], v[174:177], v[236:239], v[12:15]
	v_mfma_f32_16x16x32_bf16 v[8:11], v[212:215], v[236:239], v[8:11]
	v_mfma_f32_16x16x32_bf16 v[4:7], v[174:177], v[244:247], v[4:7]
	v_mfma_f32_16x16x32_bf16 v[0:3], v[212:215], v[244:247], v[0:3]
	v_mfma_f32_16x16x32_bf16 v[30:33], v[178:181], v[224:227], v[30:33]
	v_mfma_f32_16x16x32_bf16 v[26:29], v[216:219], v[224:227], v[26:29]
	v_mfma_f32_16x16x32_bf16 v[22:25], v[178:181], v[232:235], v[22:25]
	v_mfma_f32_16x16x32_bf16 v[18:21], v[216:219], v[232:235], v[18:21]
	v_mfma_f32_16x16x32_bf16 v[12:15], v[178:181], v[240:243], v[12:15]
	v_mfma_f32_16x16x32_bf16 v[8:11], v[216:219], v[240:243], v[8:11]
	v_mfma_f32_16x16x32_bf16 v[4:7], v[178:181], v[248:251], v[4:7]
	v_mfma_f32_16x16x32_bf16 v[0:3], v[216:219], v[248:251], v[0:3]
	s_barrier
	s_add_i32 s63, s63, 2
	s_add_u32 s61, s61, 0x100
	s_addc_u32 s62, s62, 0
	s_add_u32 s42, s42, 0x100
	s_addc_u32 s43, s43, 0
	s_cmp_gt_u32 s63, 29
	s_cbranch_scc0 .LBB0_1623
	s_setprio 0
	s_and_b64 vcc, exec, s[20:21]
	s_cbranch_vccz .LBB0_1626
	s_barrier

.LBB0_1750:
	s_ashr_i32 s27, s26, 31
	s_lshl_b64 s[4:5], s[26:27], 20
	s_add_u32 s30, s46, s4
	s_addc_u32 s31, s47, s5
	s_and_b64 s[4:5], s[36:37], exec
	s_cselect_b32 s4, s31, s43
	s_cselect_b32 s5, s30, s42
	s_ashr_i32 s23, s22, 31
	s_lshl_b64 s[38:39], s[22:23], 20
	s_add_u32 s38, s24, s38
	s_addc_u32 s39, s48, s39
	s_and_b64 s[44:45], s[36:37], exec
	s_cselect_b32 s23, s39, s35
	s_cselect_b32 s27, s38, s34
	s_add_u32 s59, s34, 0x100
	s_addc_u32 s60, s35, 0
	s_add_u32 s42, s42, 0x80080
	v_mov_b32_e32 v0, 0
	s_addc_u32 s43, s43, 0
	s_mov_b32 s61, -2
	v_mov_b32_e32 v1, v0
	v_mov_b32_e32 v2, v0
	v_mov_b32_e32 v3, v0
	v_mov_b32_e32 v8, v0
	v_mov_b32_e32 v9, v0
	v_mov_b32_e32 v10, v0
	v_mov_b32_e32 v11, v0
	v_mov_b32_e32 v18, v0
	v_mov_b32_e32 v19, v0
	v_mov_b32_e32 v20, v0
	v_mov_b32_e32 v21, v0
	v_mov_b32_e32 v26, v0
	v_mov_b32_e32 v27, v0
	v_mov_b32_e32 v28, v0
	v_mov_b32_e32 v29, v0
	v_mov_b32_e32 v34, v0
	v_mov_b32_e32 v35, v0
	v_mov_b32_e32 v36, v0
	v_mov_b32_e32 v37, v0
	v_mov_b32_e32 v42, v0
	v_mov_b32_e32 v43, v0
	v_mov_b32_e32 v44, v0
	v_mov_b32_e32 v45, v0
	v_mov_b32_e32 v50, v0
	v_mov_b32_e32 v51, v0
	v_mov_b32_e32 v52, v0
	v_mov_b32_e32 v53, v0
	v_mov_b32_e32 v58, v0
	v_mov_b32_e32 v59, v0
	v_mov_b32_e32 v60, v0
	v_mov_b32_e32 v61, v0
	v_mov_b32_e32 v4, v0
	v_mov_b32_e32 v5, v0
	v_mov_b32_e32 v6, v0
	v_mov_b32_e32 v7, v0
	v_mov_b32_e32 v12, v0
	v_mov_b32_e32 v13, v0
	v_mov_b32_e32 v14, v0
	v_mov_b32_e32 v15, v0
	v_mov_b32_e32 v22, v0
	v_mov_b32_e32 v23, v0
	v_mov_b32_e32 v24, v0
	v_mov_b32_e32 v25, v0
	v_mov_b32_e32 v30, v0
	v_mov_b32_e32 v31, v0
	v_mov_b32_e32 v32, v0
	v_mov_b32_e32 v33, v0
	v_mov_b32_e32 v38, v0
	v_mov_b32_e32 v39, v0
	v_mov_b32_e32 v40, v0
	v_mov_b32_e32 v41, v0
	v_mov_b32_e32 v46, v0
	v_mov_b32_e32 v47, v0
	v_mov_b32_e32 v48, v0
	v_mov_b32_e32 v49, v0
	v_mov_b32_e32 v54, v0
	v_mov_b32_e32 v55, v0
	v_mov_b32_e32 v56, v0
	v_mov_b32_e32 v57, v0
	v_mov_b32_e32 v62, v0
	v_mov_b32_e32 v63, v0
	v_mov_b32_e32 v64, v0
	v_mov_b32_e32 v65, v0
	v_mov_b32_e32 v66, v0
	v_mov_b32_e32 v67, v0
	v_mov_b32_e32 v68, v0
	v_mov_b32_e32 v69, v0
	v_mov_b32_e32 v74, v0
	v_mov_b32_e32 v75, v0
	v_mov_b32_e32 v76, v0
	v_mov_b32_e32 v77, v0
	v_mov_b32_e32 v82, v0
	v_mov_b32_e32 v83, v0
	v_mov_b32_e32 v84, v0
	v_mov_b32_e32 v85, v0
	v_mov_b32_e32 v90, v0
	v_mov_b32_e32 v91, v0
	v_mov_b32_e32 v92, v0
	v_mov_b32_e32 v93, v0
	v_mov_b32_e32 v98, v0
	v_mov_b32_e32 v99, v0
	v_mov_b32_e32 v100, v0
	v_mov_b32_e32 v101, v0
	v_mov_b32_e32 v106, v0
	v_mov_b32_e32 v107, v0
	v_mov_b32_e32 v108, v0
	v_mov_b32_e32 v109, v0
	v_mov_b32_e32 v114, v0
	v_mov_b32_e32 v115, v0
	v_mov_b32_e32 v116, v0
	v_mov_b32_e32 v117, v0
	v_mov_b32_e32 v122, v0
	v_mov_b32_e32 v123, v0
	v_mov_b32_e32 v124, v0
	v_mov_b32_e32 v125, v0
	v_mov_b32_e32 v70, v0
	v_mov_b32_e32 v71, v0
	v_mov_b32_e32 v72, v0
	v_mov_b32_e32 v73, v0
	v_mov_b32_e32 v78, v0
	v_mov_b32_e32 v79, v0
	v_mov_b32_e32 v80, v0
	v_mov_b32_e32 v81, v0
	v_mov_b32_e32 v86, v0
	v_mov_b32_e32 v87, v0
	v_mov_b32_e32 v88, v0
	v_mov_b32_e32 v89, v0
	v_mov_b32_e32 v94, v0
	v_mov_b32_e32 v95, v0
	v_mov_b32_e32 v96, v0
	v_mov_b32_e32 v97, v0
	v_mov_b32_e32 v102, v0
	v_mov_b32_e32 v103, v0
	v_mov_b32_e32 v104, v0
	v_mov_b32_e32 v105, v0
	v_mov_b32_e32 v110, v0
	v_mov_b32_e32 v111, v0
	v_mov_b32_e32 v112, v0
	v_mov_b32_e32 v113, v0
	v_mov_b32_e32 v118, v0
	v_mov_b32_e32 v119, v0
	v_mov_b32_e32 v120, v0
	v_mov_b32_e32 v121, v0
	v_mov_b32_e32 v126, v0
	v_mov_b32_e32 v127, v0
	v_mov_b32_e32 v128, v0
	v_mov_b32_e32 v129, v0
	s_and_b64 vcc, exec, s[20:21]
	s_cbranch_vccnz .Lprio_skip_4
	s_setprio 1
.Lprio_skip_4:
.LBB0_1751:
	s_add_u32 s34, s42, 0xfff80080
	s_addc_u32 s35, s43, -1
	s_add_i32 s62, 0, 0x10000
	s_cmp_eq_u32 s61, 28
	s_cselect_b32 s45, s4, s35
	s_cselect_b32 s44, s5, s34
	v_add_u32_e32 v149, s62, v146
	s_cselect_b32 s35, s23, s60
	s_cselect_b32 s34, s27, s59
	s_add_i32 s64, 0, 0x14000
	ds_read_b128 v[142:145], v149
	ds_read_b128 v[160:163], v149 offset:1024
	ds_read_b128 v[164:167], v149 offset:2048
	ds_read_b128 v[168:171], v149 offset:3072
	v_add_u32_e32 v149, s64, v146
	ds_read_b128 v[172:175], v149
	ds_read_b128 v[176:179], v149 offset:1024
	ds_read_b128 v[180:183], v149 offset:2048
	ds_read_b128 v[212:215], v149 offset:3072
	v_lshl_add_u64 v[150:151], s[42:43], 0, v[140:141]
	s_add_i32 m0, s41, 0xc000
	ds_read_b128 v[216:219], v148
	ds_read_b128 v[220:223], v148 offset:1024
	ds_read_b128 v[224:227], v148 offset:2048
	ds_read_b128 v[228:231], v148 offset:3072
	ds_read_b128 v[232:235], v148 offset:4096
	ds_read_b128 v[236:239], v148 offset:5120
	ds_read_b128 v[240:243], v148 offset:6144
	ds_read_b128 v[244:247], v148 offset:7168
	global_load_lds_dwordx4 v[150:151], off
	v_lshl_add_u64 v[150:151], s[42:43], 0, v[138:139]
	s_add_i32 m0, s41, 0xe000
	s_nop 0
	global_load_lds_dwordx4 v[150:151], off
	s_waitcnt vmcnt(8)
	s_waitcnt lgkmcnt(0)
	s_barrier
	s_waitcnt lgkmcnt(0)
	v_mfma_f32_16x16x32_bf16 v[126:129], v[142:145], v[216:219], v[126:129]
	v_mfma_f32_16x16x32_bf16 v[118:121], v[164:167], v[216:219], v[118:121]
	v_mfma_f32_16x16x32_bf16 v[110:113], v[142:145], v[224:227], v[110:113]
	v_mfma_f32_16x16x32_bf16 v[102:105], v[164:167], v[224:227], v[102:105]
	v_mfma_f32_16x16x32_bf16 v[94:97], v[142:145], v[232:235], v[94:97]
	v_mfma_f32_16x16x32_bf16 v[86:89], v[164:167], v[232:235], v[86:89]
	v_mfma_f32_16x16x32_bf16 v[78:81], v[142:145], v[240:243], v[78:81]
	v_mfma_f32_16x16x32_bf16 v[70:73], v[164:167], v[240:243], v[70:73]
	v_mfma_f32_16x16x32_bf16 v[126:129], v[160:163], v[220:223], v[126:129]
	v_mfma_f32_16x16x32_bf16 v[118:121], v[168:171], v[220:223], v[118:121]
	v_mfma_f32_16x16x32_bf16 v[110:113], v[160:163], v[228:231], v[110:113]
	v_mfma_f32_16x16x32_bf16 v[102:105], v[168:171], v[228:231], v[102:105]
	v_mfma_f32_16x16x32_bf16 v[94:97], v[160:163], v[236:239], v[94:97]
	v_mfma_f32_16x16x32_bf16 v[86:89], v[168:171], v[236:239], v[86:89]
	v_mfma_f32_16x16x32_bf16 v[78:81], v[160:163], v[244:247], v[78:81]
	v_mfma_f32_16x16x32_bf16 v[70:73], v[168:171], v[244:247], v[70:73]
	v_mfma_f32_16x16x32_bf16 v[122:125], v[172:175], v[216:219], v[122:125]
	v_mfma_f32_16x16x32_bf16 v[114:117], v[180:183], v[216:219], v[114:117]
	v_mfma_f32_16x16x32_bf16 v[106:109], v[172:175], v[224:227], v[106:109]
	v_mfma_f32_16x16x32_bf16 v[98:101], v[180:183], v[224:227], v[98:101]
	v_mfma_f32_16x16x32_bf16 v[90:93], v[172:175], v[232:235], v[90:93]
	v_mfma_f32_16x16x32_bf16 v[82:85], v[180:183], v[232:235], v[82:85]
	v_mfma_f32_16x16x32_bf16 v[74:77], v[172:175], v[240:243], v[74:77]
	v_mfma_f32_16x16x32_bf16 v[66:69], v[180:183], v[240:243], v[66:69]
	v_mfma_f32_16x16x32_bf16 v[122:125], v[176:179], v[220:223], v[122:125]
	v_mfma_f32_16x16x32_bf16 v[114:117], v[212:215], v[220:223], v[114:117]
	v_mfma_f32_16x16x32_bf16 v[106:109], v[176:179], v[228:231], v[106:109]
	v_mfma_f32_16x16x32_bf16 v[98:101], v[212:215], v[228:231], v[98:101]
	v_mfma_f32_16x16x32_bf16 v[90:93], v[176:179], v[236:239], v[90:93]
	v_mfma_f32_16x16x32_bf16 v[82:85], v[212:215], v[236:239], v[82:85]
	v_mfma_f32_16x16x32_bf16 v[74:77], v[176:179], v[244:247], v[74:77]
	v_mfma_f32_16x16x32_bf16 v[66:69], v[212:215], v[244:247], v[66:69]
	s_barrier
	s_add_i32 s62, s62, s49
	v_lshl_add_u64 v[150:151], s[34:35], 0, v[134:135]
	s_mov_b32 m0, s62
	ds_read_b128 v[216:219], v148 offset:16384
	ds_read_b128 v[220:223], v148 offset:17408
	ds_read_b128 v[224:227], v148 offset:18432
	ds_read_b128 v[228:231], v148 offset:19456
	ds_read_b128 v[232:235], v148 offset:20480
	ds_read_b128 v[236:239], v148 offset:21504
	ds_read_b128 v[240:243], v148 offset:22528
	ds_read_b128 v[244:247], v148 offset:23552
	global_load_lds_dwordx4 v[150:151], off
	s_add_i32 m0, s62, 0x2000
	s_add_u32 s62, s34, 0x80000
	v_lshl_add_u64 v[152:153], s[34:35], 0, v[130:131]
	s_addc_u32 s63, s35, 0
	s_add_i32 s64, s64, s49
	global_load_lds_dwordx4 v[152:153], off
	v_lshl_add_u64 v[210:211], s[62:63], 0, v[134:135]
	s_mov_b32 m0, s64
	v_lshl_add_u64 v[248:249], s[44:45], 0, v[132:133]
	global_load_lds_dwordx4 v[210:211], off
	v_lshl_add_u64 v[210:211], s[62:63], 0, v[130:131]
	s_add_i32 m0, s64, 0x2000
	s_nop 0
	global_load_lds_dwordx4 v[210:211], off
	v_lshl_add_u64 v[210:211], s[44:45], 0, v[136:137]
	s_mov_b32 m0, s41
	s_nop 0
	global_load_lds_dwordx4 v[210:211], off
	s_mov_b32 m0, s51
	s_nop 0
	global_load_lds_dwordx4 v[248:249], off
	s_waitcnt vmcnt(8)
	s_waitcnt lgkmcnt(0)
	s_barrier
	s_waitcnt lgkmcnt(0)
	v_mfma_f32_16x16x32_bf16 v[62:65], v[142:145], v[216:219], v[62:65]
	v_mfma_f32_16x16x32_bf16 v[54:57], v[164:167], v[216:219], v[54:57]
	v_mfma_f32_16x16x32_bf16 v[46:49], v[142:145], v[224:227], v[46:49]
	v_mfma_f32_16x16x32_bf16 v[38:41], v[164:167], v[224:227], v[38:41]
	v_mfma_f32_16x16x32_bf16 v[30:33], v[142:145], v[232:235], v[30:33]
	v_mfma_f32_16x16x32_bf16 v[22:25], v[164:167], v[232:235], v[22:25]
	v_mfma_f32_16x16x32_bf16 v[12:15], v[142:145], v[240:243], v[12:15]
	v_mfma_f32_16x16x32_bf16 v[4:7], v[164:167], v[240:243], v[4:7]
	v_mfma_f32_16x16x32_bf16 v[62:65], v[160:163], v[220:223], v[62:65]
	v_mfma_f32_16x16x32_bf16 v[54:57], v[168:171], v[220:223], v[54:57]
	v_mfma_f32_16x16x32_bf16 v[46:49], v[160:163], v[228:231], v[46:49]
	v_mfma_f32_16x16x32_bf16 v[38:41], v[168:171], v[228:231], v[38:41]
	v_mfma_f32_16x16x32_bf16 v[30:33], v[160:163], v[236:239], v[30:33]
	v_mfma_f32_16x16x32_bf16 v[22:25], v[168:171], v[236:239], v[22:25]
	v_mfma_f32_16x16x32_bf16 v[12:15], v[160:163], v[244:247], v[12:15]
	v_mfma_f32_16x16x32_bf16 v[4:7], v[168:171], v[244:247], v[4:7]
	v_mfma_f32_16x16x32_bf16 v[58:61], v[172:175], v[216:219], v[58:61]
	v_mfma_f32_16x16x32_bf16 v[50:53], v[180:183], v[216:219], v[50:53]
	v_mfma_f32_16x16x32_bf16 v[42:45], v[172:175], v[224:227], v[42:45]
	v_mfma_f32_16x16x32_bf16 v[34:37], v[180:183], v[224:227], v[34:37]
	v_mfma_f32_16x16x32_bf16 v[26:29], v[172:175], v[232:235], v[26:29]
	v_mfma_f32_16x16x32_bf16 v[18:21], v[180:183], v[232:235], v[18:21]
	v_mfma_f32_16x16x32_bf16 v[8:11], v[172:175], v[240:243], v[8:11]
	v_mfma_f32_16x16x32_bf16 v[0:3], v[180:183], v[240:243], v[0:3]
	v_mfma_f32_16x16x32_bf16 v[58:61], v[176:179], v[220:223], v[58:61]
	v_mfma_f32_16x16x32_bf16 v[50:53], v[212:215], v[220:223], v[50:53]
	v_mfma_f32_16x16x32_bf16 v[42:45], v[176:179], v[228:231], v[42:45]
	v_mfma_f32_16x16x32_bf16 v[34:37], v[212:215], v[228:231], v[34:37]
	v_mfma_f32_16x16x32_bf16 v[26:29], v[176:179], v[236:239], v[26:29]
	v_mfma_f32_16x16x32_bf16 v[18:21], v[212:215], v[236:239], v[18:21]
	v_mfma_f32_16x16x32_bf16 v[8:11], v[176:179], v[244:247], v[8:11]
	v_mfma_f32_16x16x32_bf16 v[0:3], v[212:215], v[244:247], v[0:3]
	s_barrier
	s_add_i32 s62, 0, 0x18000
	v_add_u32_e32 v149, s62, v146
	s_add_i32 s63, 0, 0x1c000
	ds_read_b128 v[142:145], v149
	ds_read_b128 v[160:163], v149 offset:1024
	ds_read_b128 v[164:167], v149 offset:2048
	ds_read_b128 v[168:171], v149 offset:3072
	v_add_u32_e32 v149, s63, v146
	ds_read_b128 v[172:175], v149
	ds_read_b128 v[176:179], v149 offset:1024
	ds_read_b128 v[180:183], v149 offset:2048
	ds_read_b128 v[212:215], v149 offset:3072
	s_add_u32 s44, s44, 0x80000
	s_addc_u32 s45, s45, 0
	s_mov_b32 m0, s52
	v_lshl_add_u64 v[250:251], s[44:45], 0, v[136:137]
	ds_read_b128 v[216:219], v148 offset:32768
	ds_read_b128 v[220:223], v148 offset:33792
	ds_read_b128 v[224:227], v148 offset:34816
	ds_read_b128 v[228:231], v148 offset:35840
	ds_read_b128 v[232:235], v148 offset:36864
	ds_read_b128 v[236:239], v148 offset:37888
	ds_read_b128 v[240:243], v148 offset:38912
	ds_read_b128 v[244:247], v148 offset:39936
	global_load_lds_dwordx4 v[250:251], off
	v_lshl_add_u64 v[250:251], s[44:45], 0, v[132:133]
	s_mov_b32 m0, s53
	s_nop 0
	global_load_lds_dwordx4 v[250:251], off
	s_waitcnt vmcnt(8)
	s_waitcnt lgkmcnt(0)
	s_barrier
	s_waitcnt lgkmcnt(0)
	v_mfma_f32_16x16x32_bf16 v[126:129], v[142:145], v[216:219], v[126:129]
	v_mfma_f32_16x16x32_bf16 v[118:121], v[164:167], v[216:219], v[118:121]
	v_mfma_f32_16x16x32_bf16 v[110:113], v[142:145], v[224:227], v[110:113]
	v_mfma_f32_16x16x32_bf16 v[102:105], v[164:167], v[224:227], v[102:105]
	v_mfma_f32_16x16x32_bf16 v[94:97], v[142:145], v[232:235], v[94:97]
	v_mfma_f32_16x16x32_bf16 v[86:89], v[164:167], v[232:235], v[86:89]
	v_mfma_f32_16x16x32_bf16 v[78:81], v[142:145], v[240:243], v[78:81]
	v_mfma_f32_16x16x32_bf16 v[70:73], v[164:167], v[240:243], v[70:73]
	v_mfma_f32_16x16x32_bf16 v[126:129], v[160:163], v[220:223], v[126:129]
	v_mfma_f32_16x16x32_bf16 v[118:121], v[168:171], v[220:223], v[118:121]
	v_mfma_f32_16x16x32_bf16 v[110:113], v[160:163], v[228:231], v[110:113]
	v_mfma_f32_16x16x32_bf16 v[102:105], v[168:171], v[228:231], v[102:105]
	v_mfma_f32_16x16x32_bf16 v[94:97], v[160:163], v[236:239], v[94:97]
	v_mfma_f32_16x16x32_bf16 v[86:89], v[168:171], v[236:239], v[86:89]
	v_mfma_f32_16x16x32_bf16 v[78:81], v[160:163], v[244:247], v[78:81]
	v_mfma_f32_16x16x32_bf16 v[70:73], v[168:171], v[244:247], v[70:73]
	v_mfma_f32_16x16x32_bf16 v[122:125], v[172:175], v[216:219], v[122:125]
	v_mfma_f32_16x16x32_bf16 v[114:117], v[180:183], v[216:219], v[114:117]
	v_mfma_f32_16x16x32_bf16 v[106:109], v[172:175], v[224:227], v[106:109]
	v_mfma_f32_16x16x32_bf16 v[98:101], v[180:183], v[224:227], v[98:101]
	v_mfma_f32_16x16x32_bf16 v[90:93], v[172:175], v[232:235], v[90:93]
	v_mfma_f32_16x16x32_bf16 v[82:85], v[180:183], v[232:235], v[82:85]
	v_mfma_f32_16x16x32_bf16 v[74:77], v[172:175], v[240:243], v[74:77]
	v_mfma_f32_16x16x32_bf16 v[66:69], v[180:183], v[240:243], v[66:69]
	v_mfma_f32_16x16x32_bf16 v[122:125], v[176:179], v[220:223], v[122:125]
	v_mfma_f32_16x16x32_bf16 v[114:117], v[212:215], v[220:223], v[114:117]
	v_mfma_f32_16x16x32_bf16 v[106:109], v[176:179], v[228:231], v[106:109]
	v_mfma_f32_16x16x32_bf16 v[98:101], v[212:215], v[228:231], v[98:101]
	v_mfma_f32_16x16x32_bf16 v[90:93], v[176:179], v[236:239], v[90:93]
	v_mfma_f32_16x16x32_bf16 v[82:85], v[212:215], v[236:239], v[82:85]
	v_mfma_f32_16x16x32_bf16 v[74:77], v[176:179], v[244:247], v[74:77]
	v_mfma_f32_16x16x32_bf16 v[66:69], v[212:215], v[244:247], v[66:69]
	s_barrier
	s_add_i32 s44, s62, s49
	v_lshl_add_u64 v[150:151], v[150:151], 0, s[96:97]
	s_mov_b32 m0, s44
	ds_read_b128 v[216:219], v148 offset:49152
	ds_read_b128 v[220:223], v148 offset:50176
	ds_read_b128 v[224:227], v148 offset:51200
	ds_read_b128 v[228:231], v148 offset:52224
	ds_read_b128 v[232:235], v148 offset:53248
	ds_read_b128 v[236:239], v148 offset:54272
	ds_read_b128 v[240:243], v148 offset:55296
	ds_read_b128 v[244:247], v148 offset:56320
	global_load_lds_dwordx4 v[150:151], off
	s_add_i32 m0, s44, 0x2000
	s_add_u32 s34, s34, 0x80080
	v_lshl_add_u64 v[150:151], v[152:153], 0, s[96:97]
	s_addc_u32 s35, s35, 0
	s_add_i32 s44, s63, s49
	global_load_lds_dwordx4 v[150:151], off
	v_lshl_add_u64 v[150:151], s[34:35], 0, v[134:135]
	s_mov_b32 m0, s44
	s_nop 0
	global_load_lds_dwordx4 v[150:151], off
	v_lshl_add_u64 v[150:151], s[34:35], 0, v[130:131]
	s_add_i32 m0, s44, 0x2000
	s_nop 0
	global_load_lds_dwordx4 v[150:151], off
	v_lshl_add_u64 v[150:151], v[210:211], 0, s[96:97]
	s_mov_b32 m0, s54
	s_nop 0
	global_load_lds_dwordx4 v[150:151], off
	v_lshl_add_u64 v[150:151], v[248:249], 0, s[96:97]
	s_mov_b32 m0, s55
	s_nop 0
	global_load_lds_dwordx4 v[150:151], off
	s_waitcnt vmcnt(8)
	s_waitcnt lgkmcnt(0)
	s_barrier
	s_waitcnt lgkmcnt(0)
	v_mfma_f32_16x16x32_bf16 v[62:65], v[142:145], v[216:219], v[62:65]
	v_mfma_f32_16x16x32_bf16 v[54:57], v[164:167], v[216:219], v[54:57]
	v_mfma_f32_16x16x32_bf16 v[46:49], v[142:145], v[224:227], v[46:49]
	v_mfma_f32_16x16x32_bf16 v[38:41], v[164:167], v[224:227], v[38:41]
	v_mfma_f32_16x16x32_bf16 v[30:33], v[142:145], v[232:235], v[30:33]
	v_mfma_f32_16x16x32_bf16 v[22:25], v[164:167], v[232:235], v[22:25]
	v_mfma_f32_16x16x32_bf16 v[12:15], v[142:145], v[240:243], v[12:15]
	v_mfma_f32_16x16x32_bf16 v[4:7], v[164:167], v[240:243], v[4:7]
	v_mfma_f32_16x16x32_bf16 v[62:65], v[160:163], v[220:223], v[62:65]
	v_mfma_f32_16x16x32_bf16 v[54:57], v[168:171], v[220:223], v[54:57]
	v_mfma_f32_16x16x32_bf16 v[46:49], v[160:163], v[228:231], v[46:49]
	v_mfma_f32_16x16x32_bf16 v[38:41], v[168:171], v[228:231], v[38:41]
	v_mfma_f32_16x16x32_bf16 v[30:33], v[160:163], v[236:239], v[30:33]
	v_mfma_f32_16x16x32_bf16 v[22:25], v[168:171], v[236:239], v[22:25]
	v_mfma_f32_16x16x32_bf16 v[12:15], v[160:163], v[244:247], v[12:15]
	v_mfma_f32_16x16x32_bf16 v[4:7], v[168:171], v[244:247], v[4:7]
	v_mfma_f32_16x16x32_bf16 v[58:61], v[172:175], v[216:219], v[58:61]
	v_mfma_f32_16x16x32_bf16 v[50:53], v[180:183], v[216:219], v[50:53]
	v_mfma_f32_16x16x32_bf16 v[42:45], v[172:175], v[224:227], v[42:45]
	v_mfma_f32_16x16x32_bf16 v[34:37], v[180:183], v[224:227], v[34:37]
	v_mfma_f32_16x16x32_bf16 v[26:29], v[172:175], v[232:235], v[26:29]
	v_mfma_f32_16x16x32_bf16 v[18:21], v[180:183], v[232:235], v[18:21]
	v_mfma_f32_16x16x32_bf16 v[8:11], v[172:175], v[240:243], v[8:11]
	v_mfma_f32_16x16x32_bf16 v[0:3], v[180:183], v[240:243], v[0:3]
	v_mfma_f32_16x16x32_bf16 v[58:61], v[176:179], v[220:223], v[58:61]
	v_mfma_f32_16x16x32_bf16 v[50:53], v[212:215], v[220:223], v[50:53]
	v_mfma_f32_16x16x32_bf16 v[42:45], v[176:179], v[228:231], v[42:45]
	v_mfma_f32_16x16x32_bf16 v[34:37], v[212:215], v[228:231], v[34:37]
	v_mfma_f32_16x16x32_bf16 v[26:29], v[176:179], v[236:239], v[26:29]
	v_mfma_f32_16x16x32_bf16 v[18:21], v[212:215], v[236:239], v[18:21]
	v_mfma_f32_16x16x32_bf16 v[8:11], v[176:179], v[244:247], v[8:11]
	v_mfma_f32_16x16x32_bf16 v[0:3], v[212:215], v[244:247], v[0:3]
	s_barrier
	s_add_i32 s61, s61, 2
	s_add_u32 s59, s59, 0x100
	s_addc_u32 s60, s60, 0
	s_add_u32 s42, s42, 0x100
	s_addc_u32 s43, s43, 0
	s_cmp_gt_u32 s61, 29
	s_cbranch_scc0 .LBB0_1751
	s_setprio 0
	s_and_b64 vcc, exec, s[20:21]
	s_cbranch_vccz .LBB0_1754
	s_barrier

.LBB0_1829:
	s_add_u32 s4, s34, 0x100
	v_mov_b32_e32 v0, 0
	s_addc_u32 s5, s35, 0
	s_mov_b32 s61, -2
	v_mov_b32_e32 v1, v0
	v_mov_b32_e32 v2, v0
	v_mov_b32_e32 v3, v0
	v_mov_b32_e32 v4, v0
	v_mov_b32_e32 v5, v0
	v_mov_b32_e32 v6, v0
	v_mov_b32_e32 v7, v0
	v_mov_b32_e32 v8, v0
	v_mov_b32_e32 v9, v0
	v_mov_b32_e32 v10, v0
	v_mov_b32_e32 v11, v0
	v_mov_b32_e32 v12, v0
	v_mov_b32_e32 v13, v0
	v_mov_b32_e32 v14, v0
	v_mov_b32_e32 v15, v0
	v_mov_b32_e32 v18, v0
	v_mov_b32_e32 v19, v0
	v_mov_b32_e32 v20, v0
	v_mov_b32_e32 v21, v0
	v_mov_b32_e32 v22, v0
	v_mov_b32_e32 v23, v0
	v_mov_b32_e32 v24, v0
	v_mov_b32_e32 v25, v0
	v_mov_b32_e32 v26, v0
	v_mov_b32_e32 v27, v0
	v_mov_b32_e32 v28, v0
	v_mov_b32_e32 v29, v0
	v_mov_b32_e32 v30, v0
	v_mov_b32_e32 v31, v0
	v_mov_b32_e32 v32, v0
	v_mov_b32_e32 v33, v0
	v_mov_b32_e32 v66, v0
	v_mov_b32_e32 v67, v0
	v_mov_b32_e32 v68, v0
	v_mov_b32_e32 v69, v0
	v_mov_b32_e32 v70, v0
	v_mov_b32_e32 v71, v0
	v_mov_b32_e32 v72, v0
	v_mov_b32_e32 v73, v0
	v_mov_b32_e32 v74, v0
	v_mov_b32_e32 v75, v0
	v_mov_b32_e32 v76, v0
	v_mov_b32_e32 v77, v0
	v_mov_b32_e32 v78, v0
	v_mov_b32_e32 v79, v0
	v_mov_b32_e32 v80, v0
	v_mov_b32_e32 v81, v0
	v_mov_b32_e32 v82, v0
	v_mov_b32_e32 v83, v0
	v_mov_b32_e32 v84, v0
	v_mov_b32_e32 v85, v0
	v_mov_b32_e32 v86, v0
	v_mov_b32_e32 v87, v0
	v_mov_b32_e32 v88, v0
	v_mov_b32_e32 v89, v0
	v_mov_b32_e32 v90, v0
	v_mov_b32_e32 v91, v0
	v_mov_b32_e32 v92, v0
	v_mov_b32_e32 v93, v0
	v_mov_b32_e32 v94, v0
	v_mov_b32_e32 v95, v0
	v_mov_b32_e32 v96, v0
	v_mov_b32_e32 v97, v0
	v_mov_b32_e32 v34, v0
	v_mov_b32_e32 v35, v0
	v_mov_b32_e32 v36, v0
	v_mov_b32_e32 v37, v0
	v_mov_b32_e32 v38, v0
	v_mov_b32_e32 v39, v0
	v_mov_b32_e32 v40, v0
	v_mov_b32_e32 v41, v0
	v_mov_b32_e32 v42, v0
	v_mov_b32_e32 v43, v0
	v_mov_b32_e32 v44, v0
	v_mov_b32_e32 v45, v0
	v_mov_b32_e32 v46, v0
	v_mov_b32_e32 v47, v0
	v_mov_b32_e32 v48, v0
	v_mov_b32_e32 v49, v0
	v_mov_b32_e32 v50, v0
	v_mov_b32_e32 v51, v0
	v_mov_b32_e32 v52, v0
	v_mov_b32_e32 v53, v0
	v_mov_b32_e32 v54, v0
	v_mov_b32_e32 v55, v0
	v_mov_b32_e32 v56, v0
	v_mov_b32_e32 v57, v0
	v_mov_b32_e32 v58, v0
	v_mov_b32_e32 v59, v0
	v_mov_b32_e32 v60, v0
	v_mov_b32_e32 v61, v0
	v_mov_b32_e32 v62, v0
	v_mov_b32_e32 v63, v0
	v_mov_b32_e32 v64, v0
	v_mov_b32_e32 v65, v0
	v_mov_b32_e32 v98, v0
	v_mov_b32_e32 v99, v0
	v_mov_b32_e32 v100, v0
	v_mov_b32_e32 v101, v0
	v_mov_b32_e32 v102, v0
	v_mov_b32_e32 v103, v0
	v_mov_b32_e32 v104, v0
	v_mov_b32_e32 v105, v0
	v_mov_b32_e32 v106, v0
	v_mov_b32_e32 v107, v0
	v_mov_b32_e32 v108, v0
	v_mov_b32_e32 v109, v0
	v_mov_b32_e32 v110, v0
	v_mov_b32_e32 v111, v0
	v_mov_b32_e32 v112, v0
	v_mov_b32_e32 v113, v0
	v_mov_b32_e32 v114, v0
	v_mov_b32_e32 v115, v0
	v_mov_b32_e32 v116, v0
	v_mov_b32_e32 v117, v0
	v_mov_b32_e32 v118, v0
	v_mov_b32_e32 v119, v0
	v_mov_b32_e32 v120, v0
	v_mov_b32_e32 v121, v0
	v_mov_b32_e32 v122, v0
	v_mov_b32_e32 v123, v0
	v_mov_b32_e32 v124, v0
	v_mov_b32_e32 v125, v0
	v_mov_b32_e32 v126, v0
	v_mov_b32_e32 v127, v0
	v_mov_b32_e32 v128, v0
	v_mov_b32_e32 v129, v0
	s_and_b64 vcc, exec, s[20:21]
	s_cbranch_vccnz .Lprio_skip_5
	s_setprio 1
.Lprio_skip_5:
.LBB0_1830:
	s_add_u32 s34, s30, 0x100
	s_addc_u32 s35, s31, 0
	s_add_i32 s62, 0, 0x10000
	s_cmpk_eq_i32 s61, 0x54
	s_cselect_b32 s41, s23, s35
	s_cselect_b32 s40, s22, s34
	v_add_u32_e32 v150, s62, v166
	s_cselect_b32 s39, s27, s5
	s_cselect_b32 s38, s26, s4
	s_add_i32 s63, 0, 0x14000
	ds_read_b128 v[142:145], v150
	ds_read_b128 v[146:149], v150 offset:1024
	ds_read_b128 v[160:163], v150 offset:2048
	ds_read_b128 v[170:173], v150 offset:3072
	v_add_u32_e32 v150, s63, v166
	ds_read_b128 v[174:177], v150
	ds_read_b128 v[178:181], v150 offset:1024
	ds_read_b128 v[212:215], v150 offset:2048
	ds_read_b128 v[216:219], v150 offset:3072
	v_lshl_add_u64 v[150:151], s[30:31], 0, v[140:141]
	s_add_i32 m0, s48, 0xc000
	ds_read_b128 v[220:223], v168
	ds_read_b128 v[224:227], v168 offset:1024
	ds_read_b128 v[228:231], v168 offset:2048
	ds_read_b128 v[232:235], v168 offset:3072
	ds_read_b128 v[236:239], v168 offset:4096
	ds_read_b128 v[240:243], v168 offset:5120
	ds_read_b128 v[244:247], v168 offset:6144
	ds_read_b128 v[248:251], v168 offset:7168
	global_load_lds_dwordx4 v[150:151], off
	v_lshl_add_u64 v[150:151], s[30:31], 0, v[138:139]
	s_add_i32 m0, s48, 0xe000
	s_nop 0
	global_load_lds_dwordx4 v[150:151], off
	s_waitcnt vmcnt(8)
	s_waitcnt lgkmcnt(0)
	s_barrier
	s_waitcnt lgkmcnt(0)
	v_mfma_f32_16x16x32_bf16 v[126:129], v[142:145], v[220:223], v[126:129]
	v_mfma_f32_16x16x32_bf16 v[122:125], v[160:163], v[220:223], v[122:125]
	v_mfma_f32_16x16x32_bf16 v[118:121], v[142:145], v[228:231], v[118:121]
	v_mfma_f32_16x16x32_bf16 v[114:117], v[160:163], v[228:231], v[114:117]
	v_mfma_f32_16x16x32_bf16 v[110:113], v[142:145], v[236:239], v[110:113]
	v_mfma_f32_16x16x32_bf16 v[106:109], v[160:163], v[236:239], v[106:109]
	v_mfma_f32_16x16x32_bf16 v[102:105], v[142:145], v[244:247], v[102:105]
	v_mfma_f32_16x16x32_bf16 v[98:101], v[160:163], v[244:247], v[98:101]
	v_mfma_f32_16x16x32_bf16 v[126:129], v[146:149], v[224:227], v[126:129]
	v_mfma_f32_16x16x32_bf16 v[122:125], v[170:173], v[224:227], v[122:125]
	v_mfma_f32_16x16x32_bf16 v[118:121], v[146:149], v[232:235], v[118:121]
	v_mfma_f32_16x16x32_bf16 v[114:117], v[170:173], v[232:235], v[114:117]
	v_mfma_f32_16x16x32_bf16 v[110:113], v[146:149], v[240:243], v[110:113]
	v_mfma_f32_16x16x32_bf16 v[106:109], v[170:173], v[240:243], v[106:109]
	v_mfma_f32_16x16x32_bf16 v[102:105], v[146:149], v[248:251], v[102:105]
	v_mfma_f32_16x16x32_bf16 v[98:101], v[170:173], v[248:251], v[98:101]
	v_mfma_f32_16x16x32_bf16 v[62:65], v[174:177], v[220:223], v[62:65]
	v_mfma_f32_16x16x32_bf16 v[58:61], v[212:215], v[220:223], v[58:61]
	v_mfma_f32_16x16x32_bf16 v[54:57], v[174:177], v[228:231], v[54:57]
	v_mfma_f32_16x16x32_bf16 v[50:53], v[212:215], v[228:231], v[50:53]
	v_mfma_f32_16x16x32_bf16 v[46:49], v[174:177], v[236:239], v[46:49]
	v_mfma_f32_16x16x32_bf16 v[42:45], v[212:215], v[236:239], v[42:45]
	v_mfma_f32_16x16x32_bf16 v[38:41], v[174:177], v[244:247], v[38:41]
	v_mfma_f32_16x16x32_bf16 v[34:37], v[212:215], v[244:247], v[34:37]
	v_mfma_f32_16x16x32_bf16 v[62:65], v[178:181], v[224:227], v[62:65]
	v_mfma_f32_16x16x32_bf16 v[58:61], v[216:219], v[224:227], v[58:61]
	v_mfma_f32_16x16x32_bf16 v[54:57], v[178:181], v[232:235], v[54:57]
	v_mfma_f32_16x16x32_bf16 v[50:53], v[216:219], v[232:235], v[50:53]
	v_mfma_f32_16x16x32_bf16 v[46:49], v[178:181], v[240:243], v[46:49]
	v_mfma_f32_16x16x32_bf16 v[42:45], v[216:219], v[240:243], v[42:45]
	v_mfma_f32_16x16x32_bf16 v[38:41], v[178:181], v[248:251], v[38:41]
	v_mfma_f32_16x16x32_bf16 v[34:37], v[216:219], v[248:251], v[34:37]
	s_barrier
	s_add_i32 s30, s62, s47
	v_lshl_add_u64 v[150:151], s[38:39], 0, v[132:133]
	s_mov_b32 m0, s30
	ds_read_b128 v[220:223], v168 offset:16384
	ds_read_b128 v[224:227], v168 offset:17408
	ds_read_b128 v[228:231], v168 offset:18432
	ds_read_b128 v[232:235], v168 offset:19456
	ds_read_b128 v[236:239], v168 offset:20480
	ds_read_b128 v[240:243], v168 offset:21504
	ds_read_b128 v[244:247], v168 offset:22528
	ds_read_b128 v[248:251], v168 offset:23552
	global_load_lds_dwordx4 v[150:151], off
	s_add_i32 m0, s30, 0x2000
	s_add_u32 s30, s38, 0x160000
	v_lshl_add_u64 v[152:153], s[38:39], 0, v[136:137]
	s_addc_u32 s31, s39, 0
	s_add_i32 s62, s63, s47
	global_load_lds_dwordx4 v[152:153], off
	v_lshl_add_u64 v[164:165], s[30:31], 0, v[132:133]
	s_mov_b32 m0, s62
	v_lshl_add_u64 v[182:183], s[40:41], 0, v[134:135]
	global_load_lds_dwordx4 v[164:165], off
	v_lshl_add_u64 v[164:165], s[30:31], 0, v[136:137]
	s_add_i32 m0, s62, 0x2000
	s_nop 0
	global_load_lds_dwordx4 v[164:165], off
	v_lshl_add_u64 v[164:165], s[40:41], 0, v[130:131]
	s_mov_b32 m0, s48
	s_nop 0
	global_load_lds_dwordx4 v[164:165], off
	s_mov_b32 m0, s49
	s_nop 0
	global_load_lds_dwordx4 v[182:183], off
	s_waitcnt vmcnt(8)
	s_waitcnt lgkmcnt(0)
	s_barrier
	s_waitcnt lgkmcnt(0)
	v_mfma_f32_16x16x32_bf16 v[94:97], v[142:145], v[220:223], v[94:97]
	v_mfma_f32_16x16x32_bf16 v[90:93], v[160:163], v[220:223], v[90:93]
	v_mfma_f32_16x16x32_bf16 v[86:89], v[142:145], v[228:231], v[86:89]
	v_mfma_f32_16x16x32_bf16 v[82:85], v[160:163], v[228:231], v[82:85]
	v_mfma_f32_16x16x32_bf16 v[78:81], v[142:145], v[236:239], v[78:81]
	v_mfma_f32_16x16x32_bf16 v[74:77], v[160:163], v[236:239], v[74:77]
	v_mfma_f32_16x16x32_bf16 v[70:73], v[142:145], v[244:247], v[70:73]
	v_mfma_f32_16x16x32_bf16 v[66:69], v[160:163], v[244:247], v[66:69]
	v_mfma_f32_16x16x32_bf16 v[94:97], v[146:149], v[224:227], v[94:97]
	v_mfma_f32_16x16x32_bf16 v[90:93], v[170:173], v[224:227], v[90:93]
	v_mfma_f32_16x16x32_bf16 v[86:89], v[146:149], v[232:235], v[86:89]
	v_mfma_f32_16x16x32_bf16 v[82:85], v[170:173], v[232:235], v[82:85]
	v_mfma_f32_16x16x32_bf16 v[78:81], v[146:149], v[240:243], v[78:81]
	v_mfma_f32_16x16x32_bf16 v[74:77], v[170:173], v[240:243], v[74:77]
	v_mfma_f32_16x16x32_bf16 v[70:73], v[146:149], v[248:251], v[70:73]
	v_mfma_f32_16x16x32_bf16 v[66:69], v[170:173], v[248:251], v[66:69]
	v_mfma_f32_16x16x32_bf16 v[30:33], v[174:177], v[220:223], v[30:33]
	v_mfma_f32_16x16x32_bf16 v[26:29], v[212:215], v[220:223], v[26:29]
	v_mfma_f32_16x16x32_bf16 v[22:25], v[174:177], v[228:231], v[22:25]
	v_mfma_f32_16x16x32_bf16 v[18:21], v[212:215], v[228:231], v[18:21]
	v_mfma_f32_16x16x32_bf16 v[12:15], v[174:177], v[236:239], v[12:15]
	v_mfma_f32_16x16x32_bf16 v[8:11], v[212:215], v[236:239], v[8:11]
	v_mfma_f32_16x16x32_bf16 v[4:7], v[174:177], v[244:247], v[4:7]
	v_mfma_f32_16x16x32_bf16 v[0:3], v[212:215], v[244:247], v[0:3]
	v_mfma_f32_16x16x32_bf16 v[30:33], v[178:181], v[224:227], v[30:33]
	v_mfma_f32_16x16x32_bf16 v[26:29], v[216:219], v[224:227], v[26:29]
	v_mfma_f32_16x16x32_bf16 v[22:25], v[178:181], v[232:235], v[22:25]
	v_mfma_f32_16x16x32_bf16 v[18:21], v[216:219], v[232:235], v[18:21]
	v_mfma_f32_16x16x32_bf16 v[12:15], v[178:181], v[240:243], v[12:15]
	v_mfma_f32_16x16x32_bf16 v[8:11], v[216:219], v[240:243], v[8:11]
	v_mfma_f32_16x16x32_bf16 v[4:7], v[178:181], v[248:251], v[4:7]
	v_mfma_f32_16x16x32_bf16 v[0:3], v[216:219], v[248:251], v[0:3]
	s_barrier
	s_add_i32 s62, 0, 0x18000
	v_add_u32_e32 v169, s62, v166
	s_add_i32 s63, 0, 0x1c000
	ds_read_b128 v[142:145], v169
	ds_read_b128 v[146:149], v169 offset:1024
	ds_read_b128 v[160:163], v169 offset:2048
	ds_read_b128 v[170:173], v169 offset:3072
	v_add_u32_e32 v169, s63, v166
	ds_read_b128 v[174:177], v169
	ds_read_b128 v[178:181], v169 offset:1024
	ds_read_b128 v[212:215], v169 offset:2048
	ds_read_b128 v[216:219], v169 offset:3072
	s_add_u32 s30, s40, 0x160000
	s_addc_u32 s31, s41, 0
	s_mov_b32 m0, s50
	v_lshl_add_u64 v[210:211], s[30:31], 0, v[130:131]
	ds_read_b128 v[220:223], v168 offset:32768
	ds_read_b128 v[224:227], v168 offset:33792
	ds_read_b128 v[228:231], v168 offset:34816
	ds_read_b128 v[232:235], v168 offset:35840
	ds_read_b128 v[236:239], v168 offset:36864
	ds_read_b128 v[240:243], v168 offset:37888
	ds_read_b128 v[244:247], v168 offset:38912
	ds_read_b128 v[248:251], v168 offset:39936
	global_load_lds_dwordx4 v[210:211], off
	v_lshl_add_u64 v[210:211], s[30:31], 0, v[134:135]
	s_mov_b32 m0, s51
	s_nop 0
	global_load_lds_dwordx4 v[210:211], off
	s_waitcnt vmcnt(8)
	s_waitcnt lgkmcnt(0)
	s_barrier
	s_waitcnt lgkmcnt(0)
	v_mfma_f32_16x16x32_bf16 v[126:129], v[142:145], v[220:223], v[126:129]
	v_mfma_f32_16x16x32_bf16 v[122:125], v[160:163], v[220:223], v[122:125]
	v_mfma_f32_16x16x32_bf16 v[118:121], v[142:145], v[228:231], v[118:121]
	v_mfma_f32_16x16x32_bf16 v[114:117], v[160:163], v[228:231], v[114:117]
	v_mfma_f32_16x16x32_bf16 v[110:113], v[142:145], v[236:239], v[110:113]
	v_mfma_f32_16x16x32_bf16 v[106:109], v[160:163], v[236:239], v[106:109]
	v_mfma_f32_16x16x32_bf16 v[102:105], v[142:145], v[244:247], v[102:105]
	v_mfma_f32_16x16x32_bf16 v[98:101], v[160:163], v[244:247], v[98:101]
	v_mfma_f32_16x16x32_bf16 v[126:129], v[146:149], v[224:227], v[126:129]
	v_mfma_f32_16x16x32_bf16 v[122:125], v[170:173], v[224:227], v[122:125]
	v_mfma_f32_16x16x32_bf16 v[118:121], v[146:149], v[232:235], v[118:121]
	v_mfma_f32_16x16x32_bf16 v[114:117], v[170:173], v[232:235], v[114:117]
	v_mfma_f32_16x16x32_bf16 v[110:113], v[146:149], v[240:243], v[110:113]
	v_mfma_f32_16x16x32_bf16 v[106:109], v[170:173], v[240:243], v[106:109]
	v_mfma_f32_16x16x32_bf16 v[102:105], v[146:149], v[248:251], v[102:105]
	v_mfma_f32_16x16x32_bf16 v[98:101], v[170:173], v[248:251], v[98:101]
	v_mfma_f32_16x16x32_bf16 v[62:65], v[174:177], v[220:223], v[62:65]
	v_mfma_f32_16x16x32_bf16 v[58:61], v[212:215], v[220:223], v[58:61]
	v_mfma_f32_16x16x32_bf16 v[54:57], v[174:177], v[228:231], v[54:57]
	v_mfma_f32_16x16x32_bf16 v[50:53], v[212:215], v[228:231], v[50:53]
	v_mfma_f32_16x16x32_bf16 v[46:49], v[174:177], v[236:239], v[46:49]
	v_mfma_f32_16x16x32_bf16 v[42:45], v[212:215], v[236:239], v[42:45]
	v_mfma_f32_16x16x32_bf16 v[38:41], v[174:177], v[244:247], v[38:41]
	v_mfma_f32_16x16x32_bf16 v[34:37], v[212:215], v[244:247], v[34:37]
	v_mfma_f32_16x16x32_bf16 v[62:65], v[178:181], v[224:227], v[62:65]
	v_mfma_f32_16x16x32_bf16 v[58:61], v[216:219], v[224:227], v[58:61]
	v_mfma_f32_16x16x32_bf16 v[54:57], v[178:181], v[232:235], v[54:57]
	v_mfma_f32_16x16x32_bf16 v[50:53], v[216:219], v[232:235], v[50:53]
	v_mfma_f32_16x16x32_bf16 v[46:49], v[178:181], v[240:243], v[46:49]
	v_mfma_f32_16x16x32_bf16 v[42:45], v[216:219], v[240:243], v[42:45]
	v_mfma_f32_16x16x32_bf16 v[38:41], v[178:181], v[248:251], v[38:41]
	v_mfma_f32_16x16x32_bf16 v[34:37], v[216:219], v[248:251], v[34:37]
	s_barrier
	s_add_i32 s30, s62, s47
	v_lshl_add_u64 v[150:151], v[150:151], 0, s[96:97]
	s_mov_b32 m0, s30
	ds_read_b128 v[220:223], v168 offset:49152
	ds_read_b128 v[224:227], v168 offset:50176
	ds_read_b128 v[228:231], v168 offset:51200
	ds_read_b128 v[232:235], v168 offset:52224
	ds_read_b128 v[236:239], v168 offset:53248
	ds_read_b128 v[240:243], v168 offset:54272
	ds_read_b128 v[244:247], v168 offset:55296
	ds_read_b128 v[248:251], v168 offset:56320
	global_load_lds_dwordx4 v[150:151], off
	s_add_i32 m0, s30, 0x2000
	s_add_u32 s30, s38, 0x160080
	v_lshl_add_u64 v[150:151], v[152:153], 0, s[96:97]
	s_addc_u32 s31, s39, 0
	s_add_i32 s38, s63, s47
	global_load_lds_dwordx4 v[150:151], off
	v_lshl_add_u64 v[150:151], s[30:31], 0, v[132:133]
	s_mov_b32 m0, s38
	s_nop 0
	global_load_lds_dwordx4 v[150:151], off
	v_lshl_add_u64 v[150:151], s[30:31], 0, v[136:137]
	s_add_i32 m0, s38, 0x2000
	s_nop 0
	global_load_lds_dwordx4 v[150:151], off
	v_lshl_add_u64 v[150:151], v[164:165], 0, s[96:97]
	s_mov_b32 m0, s53
	s_nop 0
	global_load_lds_dwordx4 v[150:151], off
	v_lshl_add_u64 v[150:151], v[182:183], 0, s[96:97]
	s_mov_b32 m0, s54
	s_nop 0
	global_load_lds_dwordx4 v[150:151], off
	s_waitcnt vmcnt(8)
	s_waitcnt lgkmcnt(0)
	s_barrier
	s_waitcnt lgkmcnt(0)
	v_mfma_f32_16x16x32_bf16 v[94:97], v[142:145], v[220:223], v[94:97]
	v_mfma_f32_16x16x32_bf16 v[90:93], v[160:163], v[220:223], v[90:93]
	v_mfma_f32_16x16x32_bf16 v[86:89], v[142:145], v[228:231], v[86:89]
	v_mfma_f32_16x16x32_bf16 v[82:85], v[160:163], v[228:231], v[82:85]
	v_mfma_f32_16x16x32_bf16 v[78:81], v[142:145], v[236:239], v[78:81]
	v_mfma_f32_16x16x32_bf16 v[74:77], v[160:163], v[236:239], v[74:77]
	v_mfma_f32_16x16x32_bf16 v[70:73], v[142:145], v[244:247], v[70:73]
	v_mfma_f32_16x16x32_bf16 v[66:69], v[160:163], v[244:247], v[66:69]
	v_mfma_f32_16x16x32_bf16 v[94:97], v[146:149], v[224:227], v[94:97]
	v_mfma_f32_16x16x32_bf16 v[90:93], v[170:173], v[224:227], v[90:93]
	v_mfma_f32_16x16x32_bf16 v[86:89], v[146:149], v[232:235], v[86:89]
	v_mfma_f32_16x16x32_bf16 v[82:85], v[170:173], v[232:235], v[82:85]
	v_mfma_f32_16x16x32_bf16 v[78:81], v[146:149], v[240:243], v[78:81]
	v_mfma_f32_16x16x32_bf16 v[74:77], v[170:173], v[240:243], v[74:77]
	v_mfma_f32_16x16x32_bf16 v[70:73], v[146:149], v[248:251], v[70:73]
	v_mfma_f32_16x16x32_bf16 v[66:69], v[170:173], v[248:251], v[66:69]
	v_mfma_f32_16x16x32_bf16 v[30:33], v[174:177], v[220:223], v[30:33]
	v_mfma_f32_16x16x32_bf16 v[26:29], v[212:215], v[220:223], v[26:29]
	v_mfma_f32_16x16x32_bf16 v[22:25], v[174:177], v[228:231], v[22:25]
	v_mfma_f32_16x16x32_bf16 v[18:21], v[212:215], v[228:231], v[18:21]
	v_mfma_f32_16x16x32_bf16 v[12:15], v[174:177], v[236:239], v[12:15]
	v_mfma_f32_16x16x32_bf16 v[8:11], v[212:215], v[236:239], v[8:11]
	v_mfma_f32_16x16x32_bf16 v[4:7], v[174:177], v[244:247], v[4:7]
	v_mfma_f32_16x16x32_bf16 v[0:3], v[212:215], v[244:247], v[0:3]
	v_mfma_f32_16x16x32_bf16 v[30:33], v[178:181], v[224:227], v[30:33]
	v_mfma_f32_16x16x32_bf16 v[26:29], v[216:219], v[224:227], v[26:29]
	v_mfma_f32_16x16x32_bf16 v[22:25], v[178:181], v[232:235], v[22:25]
	v_mfma_f32_16x16x32_bf16 v[18:21], v[216:219], v[232:235], v[18:21]
	v_mfma_f32_16x16x32_bf16 v[12:15], v[178:181], v[240:243], v[12:15]
	v_mfma_f32_16x16x32_bf16 v[8:11], v[216:219], v[240:243], v[8:11]
	v_mfma_f32_16x16x32_bf16 v[4:7], v[178:181], v[248:251], v[4:7]
	v_mfma_f32_16x16x32_bf16 v[0:3], v[216:219], v[248:251], v[0:3]
	s_barrier
	s_add_i32 s61, s61, 2
	s_add_u32 s4, s4, 0x100
	s_addc_u32 s5, s5, 0
	s_cmpk_gt_u32 s61, 0x55
	s_mov_b64 s[30:31], s[34:35]
	s_cbranch_scc0 .LBB0_1830
	s_setprio 0
	s_and_b64 vcc, exec, s[20:21]
	s_cbranch_vccz .LBB0_1833
	s_barrier
